# plus silu/sigmoid epilogues: IEEE f32 division expansion replaced by v_rcp_f32+v_mul_f32 (f32 kept, <=1ulp before bf16 rounding)
# speedup vs baseline: 1.0501x; 1.0307x over previous
; DI void phase_ffnup(const Params& p, int layer, unsigned char* smem) {
;     ...
;       float rs = (tt[mi] >= 0 && tt[mi] < TP) ? rsqrtf(rowss[b * TP + tt[mi]] * (1.f / DM) + EPS) : 0.f;
; #pragma unroll
;       for (int ni = 0; ni < 8; ++ni) acc[ni][mi] *= rs;
; #pragma unroll
;       for (int n2 = 0; n2 < 4; ++n2) {
;         float4 g4 = make_float4(acc[2 * n2][mi][0], acc[2 * n2][mi][1], acc[2 * n2][mi][2], acc[2 * n2][mi][3]);
;         *(float4*)(G + r * 132 + gc0 + 16 * n2) = g4;
;       }
;     }
;     __syncthreads();
; #pragma unroll
;     for (int n2 = 0; n2 < 4; ++n2) {
;       const int gc = gc0 + 16 * n2;
;       const int ff = 128 * nt + gc;
;       const float4 w0 = *(const float4*)(cw + ff), w1 = *(const float4*)(cw + DFF + ff), w2 = *(const float4*)(cw + 2 * DFF + ff);
;       const float4 c4 = *(const float4*)(cb + ff);
; #pragma unroll
;       for (int mi = 0; mi < 4; ++mi) {
;         const int r = r0 + mi * 16;
;         if (r >= 2 && tt[mi] < TP) {
;           const float4 g1 = *(const float4*)(G + (r - 1) * 132 + gc);
;           const float4 g2 = *(const float4*)(G + (r - 2) * 132 + gc);
;           float cv[4];
;           cv[0] = c4.x + w0.x * g2.x + w1.x * g1.x + w2.x * acc[2 * n2][mi][0];
;           cv[1] = c4.y + w0.y * g2.y + w1.y * g1.y + w2.y * acc[2 * n2][mi][1];
;           cv[2] = c4.z + w0.z * g2.z + w1.z * g1.z + w2.z * acc[2 * n2][mi][2];
;           cv[3] = c4.w + w0.w * g2.w + w1.w * g1.w + w2.w * acc[2 * n2][mi][3];
;           float a[4];
; #pragma unroll
;           for (int e = 0; e < 4; ++e) a[e] = cv[e] / (1.f + __expf(-cv[e])) * acc[2 * n2 + 1][mi][e];
;           u32x2 pk = {pack2bf(a[0], a[1]), pack2bf(a[2], a[3])};
;           *(u32x2*)(p.act + (size_t)(b * TP + tt[mi]) * DFF + ff) = pk;
.LBB0_33:
	s_or_b64 exec, exec, s[4:5]
	v_add_u32_e32 v161, 0x2100, v164
	s_lshl_b32 s52, s34, 7
	v_pk_mul_f32 v[70:71], v[38:39], v[148:149] op_sel_hi:[1,0]
	v_pk_mul_f32 v[38:39], v[110:111], v[148:149] op_sel_hi:[1,0]
	v_add_u32_e32 v110, v146, v161
	v_add_u32_e32 v146, s52, v168
	v_pk_mul_f32 v[104:105], v[8:9], v[148:149] op_sel_hi:[1,0]
	v_pk_mul_f32 v[102:103], v[6:7], v[148:149] op_sel_hi:[1,0]
	v_ashrrev_i32_e32 v147, 31, v146
	v_pk_mul_f32 v[72:73], v[40:41], v[148:149] op_sel_hi:[1,0]
	v_pk_mul_f32 v[40:41], v[112:113], v[148:149] op_sel_hi:[1,0]
	v_pk_mul_f32 v[8:9], v[116:117], v[148:149] op_sel_hi:[1,0]
	v_pk_mul_f32 v[6:7], v[114:115], v[148:149] op_sel_hi:[1,0]
	ds_write_b128 v110, v[102:105]
	ds_write_b128 v110, v[70:73] offset:64
	ds_write_b128 v110, v[38:41] offset:128
	ds_write_b128 v110, v[6:9] offset:192
	v_lshlrev_b64 v[110:111], 2, v[146:147]
	v_lshl_add_u64 v[158:159], s[40:41], 0, v[110:111]
	v_lshl_add_u64 v[114:115], s[44:45], 0, v[110:111]
	v_lshl_add_u64 v[118:119], s[46:47], 0, v[110:111]
	s_waitcnt lgkmcnt(0)
	s_barrier
	v_lshl_add_u64 v[156:157], s[42:43], 0, v[110:111]
	global_load_dwordx4 v[110:113], v[158:159], off
	s_nop 0
	global_load_dwordx4 v[114:117], v[114:115], off
	s_nop 0
	global_load_dwordx4 v[118:121], v[118:119], off
	s_nop 0
	global_load_dwordx4 v[122:125], v[156:157], off
	s_movk_i32 s3, 0x1080
	v_cmp_lt_i32_e32 vcc, 1, v160
	v_cmp_gt_i32_e64 s[4:5], s3, v162
	v_mov_b32_e32 v155, v154
	s_and_b64 s[34:35], vcc, s[4:5]
	v_add_u32_e32 v162, s2, v162
	s_and_saveexec_b64 s[4:5], s[34:35]
	s_cbranch_execz .LBB0_35
	v_pk_mul_f32 v[180:181], v[142:143], v[154:155]
	v_lshl_add_u32 v142, v168, 2, v169
	v_mov_b32_e32 v174, v154
	v_mov_b32_e32 v175, v154
	v_add_u32_e32 v143, 0xfffffdf0, v142
	v_pk_mul_f32 v[178:179], v[144:145], v[174:175]
	v_add_u32_e32 v153, 0xfffffbe0, v142
	ds_read_b128 v[142:145], v143
	ds_read_b128 v[174:177], v153
	s_movk_i32 s3, 0x1600
	s_waitcnt vmcnt(0) lgkmcnt(0)
	v_pk_fma_f32 v[174:175], v[110:111], v[174:175], v[122:123]
	s_nop 0
	v_pk_fma_f32 v[142:143], v[114:115], v[142:143], v[174:175]
	s_nop 0
	v_pk_fma_f32 v[138:139], v[138:139], v[118:119], v[142:143]
	s_nop 0
	v_mul_f32_e32 v142, 0xbfb8aa3b, v138
	v_mul_f32_e32 v143, 0xbfb8aa3b, v139
	v_exp_f32_e32 v142, v142
	v_exp_f32_e32 v143, v143
	s_nop 0
	v_pk_add_f32 v[142:143], v[142:143], 1.0 op_sel_hi:[1,0]
	s_nop 0
	s_nop 0
	v_rcp_f32_e32 v153, v143
	s_nop 0
	v_mul_f32_e32 v139, v139, v153
	s_nop 0
	v_rcp_f32_e32 v143, v142
	s_nop 0
	v_mul_f32_e32 v138, v138, v143
	v_pk_fma_f32 v[142:143], v[112:113], v[176:177], v[124:125]
	v_pk_mul_f32 v[138:139], v[180:181], v[138:139]
	v_pk_fma_f32 v[142:143], v[116:117], v[144:145], v[142:143]
	v_cvt_pk_bf16_f32 v138, v138, v139
	v_pk_fma_f32 v[140:141], v[140:141], v[120:121], v[142:143]
	s_nop 0
	v_mul_f32_e32 v142, 0xbfb8aa3b, v140
	v_mul_f32_e32 v143, 0xbfb8aa3b, v141
	v_exp_f32_e32 v142, v142
	v_exp_f32_e32 v143, v143
	s_nop 0
	v_pk_add_f32 v[142:143], v[142:143], 1.0 op_sel_hi:[1,0]
	s_nop 0
	s_nop 0
	v_rcp_f32_e32 v144, v143
	s_nop 0
	v_mul_f32_e32 v141, v141, v144
	s_nop 0
	v_rcp_f32_e32 v143, v142
	s_nop 0
	v_mul_f32_e32 v140, v140, v143
	v_pk_mul_f32 v[140:141], v[178:179], v[140:141]
	s_nop 0
	v_cvt_pk_bf16_f32 v139, v140, v141
	v_mov_b64_e32 v[140:141], s[86:87]
	v_mad_i64_i32 v[140:141], s[48:49], v162, s3, v[140:141]
	v_lshl_add_u64 v[140:141], v[146:147], 1, v[140:141]
	global_store_dwordx2 v[140:141], v[138:139], off
.LBB0_35:
	s_or_b64 exec, exec, s[4:5]
	s_movk_i32 s3, 0x1080
	v_cmp_lt_i32_e32 vcc, -15, v160
	v_cmp_gt_i32_e64 s[4:5], s3, v151
	v_mov_b32_e32 v153, v152
	s_and_b64 s[48:49], vcc, s[4:5]
	v_add_u32_e32 v138, s2, v151
	s_and_saveexec_b64 s[4:5], s[48:49]
	s_cbranch_execz .LBB0_37
	v_pk_mul_f32 v[174:175], v[130:131], v[152:153]
	v_lshl_add_u32 v130, v168, 2, v165
	v_mov_b32_e32 v140, v152
	v_mov_b32_e32 v141, v152
	v_add_u32_e32 v131, 0xfffffdf0, v130
	v_pk_mul_f32 v[144:145], v[132:133], v[140:141]
	v_add_u32_e32 v139, 0xfffffbe0, v130
	ds_read_b128 v[130:133], v131
	ds_read_b128 v[140:143], v139
	s_movk_i32 s3, 0x1600
	s_waitcnt vmcnt(0) lgkmcnt(0)
	v_pk_fma_f32 v[140:141], v[110:111], v[140:141], v[122:123]
	s_nop 0
	v_pk_fma_f32 v[130:131], v[114:115], v[130:131], v[140:141]
	s_nop 0
	v_pk_fma_f32 v[130:131], v[134:135], v[118:119], v[130:131]
	s_nop 0
	v_mul_f32_e32 v134, 0xbfb8aa3b, v130
	v_mul_f32_e32 v135, 0xbfb8aa3b, v131
	v_exp_f32_e32 v134, v134
	v_exp_f32_e32 v135, v135
	s_nop 0
	v_pk_add_f32 v[134:135], v[134:135], 1.0 op_sel_hi:[1,0]
	s_nop 0
	s_nop 0
	v_rcp_f32_e32 v139, v135
	s_nop 0
	v_mul_f32_e32 v131, v131, v139
	s_nop 0
	v_rcp_f32_e32 v135, v134
	s_nop 0
	v_mul_f32_e32 v130, v130, v135
	v_pk_fma_f32 v[134:135], v[112:113], v[142:143], v[124:125]
	v_pk_mul_f32 v[130:131], v[174:175], v[130:131]
	v_pk_fma_f32 v[132:133], v[116:117], v[132:133], v[134:135]
	v_cvt_pk_bf16_f32 v130, v130, v131
	v_pk_fma_f32 v[132:133], v[136:137], v[120:121], v[132:133]
	s_nop 0
	v_mul_f32_e32 v134, 0xbfb8aa3b, v132
	v_mul_f32_e32 v135, 0xbfb8aa3b, v133
	v_exp_f32_e32 v134, v134
	v_exp_f32_e32 v135, v135
	s_nop 0
	v_pk_add_f32 v[134:135], v[134:135], 1.0 op_sel_hi:[1,0]
	s_nop 0
	s_nop 0
	v_rcp_f32_e32 v136, v135
	s_nop 0
	v_mul_f32_e32 v133, v133, v136
	s_nop 0
	v_rcp_f32_e32 v135, v134
	s_nop 0
	v_mul_f32_e32 v132, v132, v135
	v_pk_mul_f32 v[132:133], v[144:145], v[132:133]
	s_nop 0
	v_cvt_pk_bf16_f32 v131, v132, v133
	v_mov_b64_e32 v[132:133], s[86:87]
	v_mad_i64_i32 v[132:133], s[50:51], v138, s3, v[132:133]
	v_lshl_add_u64 v[132:133], v[146:147], 1, v[132:133]
	global_store_dwordx2 v[132:133], v[130:131], off
; DI void phase_ffnup(const Params& p, int layer, unsigned char* smem) {
;     ...
; #pragma unroll
;     for (int n2 = 0; n2 < 4; ++n2) {
;       const int gc = gc0 + 16 * n2;
;       const int ff = 128 * nt + gc;
;       const float4 w0 = *(const float4*)(cw + ff), w1 = *(const float4*)(cw + DFF + ff), w2 = *(const float4*)(cw + 2 * DFF + ff);
;       const float4 c4 = *(const float4*)(cb + ff);
; #pragma unroll
;       for (int mi = 0; mi < 4; ++mi) {
;         const int r = r0 + mi * 16;
;         if (r >= 2 && tt[mi] < TP) {
;           const float4 g1 = *(const float4*)(G + (r - 1) * 132 + gc);
;           const float4 g2 = *(const float4*)(G + (r - 2) * 132 + gc);
;           float cv[4];
;           cv[0] = c4.x + w0.x * g2.x + w1.x * g1.x + w2.x * acc[2 * n2][mi][0];
;           cv[1] = c4.y + w0.y * g2.y + w1.y * g1.y + w2.y * acc[2 * n2][mi][1];
;           cv[2] = c4.z + w0.z * g2.z + w1.z * g1.z + w2.z * acc[2 * n2][mi][2];
;           cv[3] = c4.w + w0.w * g2.w + w1.w * g1.w + w2.w * acc[2 * n2][mi][3];
;           float a[4];
; #pragma unroll
;           for (int e = 0; e < 4; ++e) a[e] = cv[e] / (1.f + __expf(-cv[e])) * acc[2 * n2 + 1][mi][e];
;           u32x2 pk = {pack2bf(a[0], a[1]), pack2bf(a[2], a[3])};
;           *(u32x2*)(p.act + (size_t)(b * TP + tt[mi]) * DFF + ff) = pk;
.LBB0_37:
	s_or_b64 exec, exec, s[4:5]
	s_movk_i32 s3, 0xffe1
	v_cmp_lt_i32_e32 vcc, s3, v160
	s_movk_i32 s3, 0x1080
	v_cmp_gt_i32_e64 s[4:5], s3, v149
	v_mov_b32_e32 v151, v150
	s_and_b64 s[50:51], vcc, s[4:5]
	v_add_u32_e32 v130, s2, v149
	s_and_saveexec_b64 s[4:5], s[50:51]
	s_cbranch_execz .LBB0_39
	v_pk_mul_f32 v[140:141], v[106:107], v[150:151]
	v_lshl_add_u32 v106, v168, 2, v164
	v_mov_b32_e32 v132, v150
	v_mov_b32_e32 v133, v150
	v_add_u32_e32 v107, 0xfffffdf0, v106
	v_pk_mul_f32 v[136:137], v[108:109], v[132:133]
	v_add_u32_e32 v131, 0xfffffbe0, v106
	ds_read_b128 v[106:109], v107
	ds_read_b128 v[132:135], v131
	s_movk_i32 s3, 0x1600
	s_waitcnt vmcnt(0) lgkmcnt(0)
	v_pk_fma_f32 v[132:133], v[110:111], v[132:133], v[122:123]
	s_nop 0
	v_pk_fma_f32 v[106:107], v[114:115], v[106:107], v[132:133]
	s_nop 0
	v_pk_fma_f32 v[106:107], v[126:127], v[118:119], v[106:107]
	s_nop 0
	v_mul_f32_e32 v126, 0xbfb8aa3b, v106
	v_mul_f32_e32 v127, 0xbfb8aa3b, v107
	v_exp_f32_e32 v126, v126
	v_exp_f32_e32 v127, v127
	s_nop 0
	v_pk_add_f32 v[126:127], v[126:127], 1.0 op_sel_hi:[1,0]
	s_nop 0
	s_nop 0
	v_rcp_f32_e32 v131, v127
	s_nop 0
	v_mul_f32_e32 v107, v107, v131
	s_nop 0
	v_rcp_f32_e32 v127, v126
	s_nop 0
	v_mul_f32_e32 v106, v106, v127
	v_pk_fma_f32 v[126:127], v[112:113], v[134:135], v[124:125]
	v_pk_mul_f32 v[106:107], v[140:141], v[106:107]
	v_pk_fma_f32 v[108:109], v[116:117], v[108:109], v[126:127]
	v_cvt_pk_bf16_f32 v106, v106, v107
	v_pk_fma_f32 v[108:109], v[128:129], v[120:121], v[108:109]
	s_nop 0
	v_mul_f32_e32 v126, 0xbfb8aa3b, v108
	v_mul_f32_e32 v127, 0xbfb8aa3b, v109
	v_exp_f32_e32 v126, v126
	v_exp_f32_e32 v127, v127
	s_nop 0
	v_pk_add_f32 v[126:127], v[126:127], 1.0 op_sel_hi:[1,0]
	s_nop 0
	s_nop 0
	v_rcp_f32_e32 v128, v127
	s_nop 0
	v_mul_f32_e32 v109, v109, v128
	s_nop 0
	v_rcp_f32_e32 v127, v126
	s_nop 0
	v_mul_f32_e32 v108, v108, v127
	v_pk_mul_f32 v[108:109], v[136:137], v[108:109]
	s_nop 0
	v_cvt_pk_bf16_f32 v107, v108, v109
	v_mov_b64_e32 v[108:109], s[86:87]
	v_mad_i64_i32 v[108:109], s[54:55], v130, s3, v[108:109]
	v_lshl_add_u64 v[108:109], v[146:147], 1, v[108:109]
	global_store_dwordx2 v[108:109], v[106:107], off
.LBB0_39:
	s_or_b64 exec, exec, s[4:5]
	s_movk_i32 s3, 0xffd1
	v_cmp_lt_i32_e32 vcc, s3, v160
	s_movk_i32 s3, 0x1080
	v_cmp_gt_i32_e64 s[4:5], s3, v170
	v_mov_b32_e32 v149, v148
	s_and_b64 s[4:5], vcc, s[4:5]
	v_add_u32_e32 v126, s2, v170
	s_and_saveexec_b64 s[2:3], s[4:5]
	s_cbranch_execz .LBB0_41
	v_mov_b32_e32 v106, v148
	v_mov_b32_e32 v107, v148
	v_pk_mul_f32 v[132:133], v[98:99], v[148:149]
	v_lshl_add_u32 v98, v168, 2, v161
	v_pk_mul_f32 v[128:129], v[100:101], v[106:107]
	v_add_u32_e32 v99, 0xfffffdf0, v98
	v_add_u32_e32 v106, 0xfffffbe0, v98
	ds_read_b128 v[98:101], v99
	ds_read_b128 v[106:109], v106
	s_movk_i32 s53, 0x1600
	s_waitcnt vmcnt(0) lgkmcnt(0)
	v_pk_fma_f32 v[106:107], v[110:111], v[106:107], v[122:123]
	s_nop 0
	v_pk_fma_f32 v[98:99], v[114:115], v[98:99], v[106:107]
	s_nop 0
	v_pk_fma_f32 v[98:99], v[102:103], v[118:119], v[98:99]
	s_nop 0
	v_mul_f32_e32 v102, 0xbfb8aa3b, v98
	v_mul_f32_e32 v103, 0xbfb8aa3b, v99
	v_exp_f32_e32 v102, v102
	v_exp_f32_e32 v103, v103
	s_nop 0
	v_pk_add_f32 v[102:103], v[102:103], 1.0 op_sel_hi:[1,0]
	s_nop 0
	s_nop 0
	v_rcp_f32_e32 v106, v103
	s_nop 0
	v_mul_f32_e32 v99, v99, v106
	s_nop 0
	v_rcp_f32_e32 v103, v102
	s_nop 0
	v_mul_f32_e32 v98, v98, v103
	v_pk_fma_f32 v[102:103], v[112:113], v[108:109], v[124:125]
	v_pk_mul_f32 v[98:99], v[132:133], v[98:99]
	v_pk_fma_f32 v[100:101], v[116:117], v[100:101], v[102:103]
	v_cvt_pk_bf16_f32 v98, v98, v99
	v_pk_fma_f32 v[100:101], v[104:105], v[120:121], v[100:101]
	s_nop 0
	v_mul_f32_e32 v102, 0xbfb8aa3b, v100
	v_mul_f32_e32 v103, 0xbfb8aa3b, v101
	v_exp_f32_e32 v102, v102
	v_exp_f32_e32 v103, v103
	s_nop 0
	v_pk_add_f32 v[102:103], v[102:103], 1.0 op_sel_hi:[1,0]
	s_nop 0
	s_nop 0
	v_rcp_f32_e32 v104, v103
	s_nop 0
	v_mul_f32_e32 v101, v101, v104
	s_nop 0
	v_rcp_f32_e32 v103, v102
	s_nop 0
	v_mul_f32_e32 v100, v100, v103
	v_pk_mul_f32 v[100:101], v[128:129], v[100:101]
	s_nop 0
	v_cvt_pk_bf16_f32 v99, v100, v101
	v_mov_b64_e32 v[100:101], s[86:87]
	v_mad_i64_i32 v[100:101], s[54:55], v126, s53, v[100:101]
	v_lshl_add_u64 v[100:101], v[146:147], 1, v[100:101]
	global_store_dwordx2 v[100:101], v[98:99], off
.LBB0_41:
	s_or_b64 exec, exec, s[2:3]
	s_waitcnt vmcnt(2)
	v_add_u32_e32 v114, 16, v168
	v_add_u32_e32 v98, s52, v114
	v_ashrrev_i32_e32 v99, 31, v98
	v_lshlrev_b64 v[98:99], 2, v[98:99]
	v_lshl_add_u64 v[102:103], s[44:45], 0, v[98:99]
	v_lshl_add_u64 v[106:107], s[46:47], 0, v[98:99]
	global_load_dwordx4 v[98:101], v[158:159], off offset:64
	s_nop 0
	global_load_dwordx4 v[102:105], v[102:103], off
	s_nop 0
	global_load_dwordx4 v[106:109], v[106:107], off
	s_nop 0
	global_load_dwordx4 v[110:113], v[156:157], off offset:64
	s_and_saveexec_b64 s[2:3], s[34:35]
	s_cbranch_execz .LBB0_45
	s_waitcnt vmcnt(4)
	v_pk_mul_f32 v[122:123], v[94:95], v[154:155]
	v_lshl_add_u32 v94, v114, 2, v169
	v_mov_b32_e32 v116, v154
	v_mov_b32_e32 v117, v154
	v_add_u32_e32 v95, 0xfffffdf0, v94
	v_pk_mul_f32 v[120:121], v[96:97], v[116:117]
	v_add_u32_e32 v115, 0xfffffbe0, v94
	ds_read_b128 v[94:97], v95
	ds_read_b128 v[116:119], v115
	s_movk_i32 s53, 0x1600
	s_waitcnt vmcnt(0) lgkmcnt(0)
	v_pk_fma_f32 v[116:117], v[98:99], v[116:117], v[110:111]
	s_nop 0
	v_pk_fma_f32 v[94:95], v[102:103], v[94:95], v[116:117]
	s_nop 0
	v_pk_fma_f32 v[90:91], v[90:91], v[106:107], v[94:95]
	s_nop 0
	v_mul_f32_e32 v94, 0xbfb8aa3b, v90
	v_mul_f32_e32 v95, 0xbfb8aa3b, v91
	v_exp_f32_e32 v94, v94
	v_exp_f32_e32 v95, v95
	s_nop 0
	v_pk_add_f32 v[94:95], v[94:95], 1.0 op_sel_hi:[1,0]
	s_nop 0
	s_nop 0
	v_rcp_f32_e32 v115, v95
	s_nop 0
	v_mul_f32_e32 v91, v91, v115
	s_nop 0
	v_rcp_f32_e32 v95, v94
	s_nop 0
	v_mul_f32_e32 v90, v90, v95
	v_pk_fma_f32 v[94:95], v[100:101], v[118:119], v[112:113]
	v_pk_mul_f32 v[90:91], v[122:123], v[90:91]
	v_pk_fma_f32 v[94:95], v[104:105], v[96:97], v[94:95]
	v_cvt_pk_bf16_f32 v90, v90, v91
	v_pk_fma_f32 v[92:93], v[92:93], v[108:109], v[94:95]
	s_nop 0
	v_mul_f32_e32 v94, 0xbfb8aa3b, v92
	v_mul_f32_e32 v95, 0xbfb8aa3b, v93
	v_exp_f32_e32 v94, v94
	v_exp_f32_e32 v95, v95
	s_nop 0
	v_pk_add_f32 v[94:95], v[94:95], 1.0 op_sel_hi:[1,0]
	s_nop 0
	s_nop 0
	v_rcp_f32_e32 v96, v95
	s_nop 0
	v_mul_f32_e32 v93, v93, v96
	s_nop 0
	v_rcp_f32_e32 v95, v94
	s_nop 0
	v_mul_f32_e32 v92, v92, v95
	v_pk_mul_f32 v[92:93], v[120:121], v[92:93]
	s_nop 0
	v_cvt_pk_bf16_f32 v91, v92, v93
	v_mov_b64_e32 v[92:93], s[86:87]
	v_mad_i64_i32 v[92:93], s[54:55], v162, s53, v[92:93]
	v_lshl_add_u64 v[92:93], v[146:147], 1, v[92:93]
	global_store_dwordx2 v[92:93], v[90:91], off offset:32
	s_or_b64 exec, exec, s[2:3]
	s_and_saveexec_b64 s[2:3], s[48:49]
	s_cbranch_execnz .LBB0_46

; DI void phase_ffnup(const Params& p, int layer, unsigned char* smem) {
;     ...
;       for (int mi = 0; mi < 4; ++mi) {
;         const int r = r0 + mi * 16;
;         if (r >= 2 && tt[mi] < TP) {
;           const float4 g1 = *(const float4*)(G + (r - 1) * 132 + gc);
;           const float4 g2 = *(const float4*)(G + (r - 2) * 132 + gc);
;           float cv[4];
;           cv[0] = c4.x + w0.x * g2.x + w1.x * g1.x + w2.x * acc[2 * n2][mi][0];
;           cv[1] = c4.y + w0.y * g2.y + w1.y * g1.y + w2.y * acc[2 * n2][mi][1];
;           cv[2] = c4.z + w0.z * g2.z + w1.z * g1.z + w2.z * acc[2 * n2][mi][2];
;           cv[3] = c4.w + w0.w * g2.w + w1.w * g1.w + w2.w * acc[2 * n2][mi][3];
;           float a[4];
; #pragma unroll
;           for (int e = 0; e < 4; ++e) a[e] = cv[e] / (1.f + __expf(-cv[e])) * acc[2 * n2 + 1][mi][e];
;           u32x2 pk = {pack2bf(a[0], a[1]), pack2bf(a[2], a[3])};
;           *(u32x2*)(p.act + (size_t)(b * TP + tt[mi]) * DFF + ff) = pk;
.LBB0_44:
	v_mov_b32_e32 v82, v150
	v_mov_b32_e32 v83, v150
	v_pk_mul_f32 v[88:89], v[74:75], v[150:151]
	v_lshl_add_u32 v74, v114, 2, v164
	v_pk_mul_f32 v[86:87], v[76:77], v[82:83]
	v_add_u32_e32 v75, 0xfffffdf0, v74
	v_add_u32_e32 v82, 0xfffffbe0, v74
	ds_read_b128 v[74:77], v75
	ds_read_b128 v[82:85], v82
	s_movk_i32 s53, 0x1600
	s_waitcnt vmcnt(0) lgkmcnt(0)
	v_pk_fma_f32 v[82:83], v[98:99], v[82:83], v[110:111]
	s_nop 0
	v_pk_fma_f32 v[74:75], v[102:103], v[74:75], v[82:83]
	s_nop 0
	v_pk_fma_f32 v[74:75], v[78:79], v[106:107], v[74:75]
	s_nop 0
	v_mul_f32_e32 v78, 0xbfb8aa3b, v74
	v_mul_f32_e32 v79, 0xbfb8aa3b, v75
	v_exp_f32_e32 v78, v78
	v_exp_f32_e32 v79, v79
	s_nop 0
	v_pk_add_f32 v[78:79], v[78:79], 1.0 op_sel_hi:[1,0]
	s_nop 0
	s_nop 0
	v_rcp_f32_e32 v82, v79
	s_nop 0
	v_mul_f32_e32 v75, v75, v82
	s_nop 0
	v_rcp_f32_e32 v79, v78
	s_nop 0
	v_mul_f32_e32 v74, v74, v79
	v_pk_fma_f32 v[78:79], v[100:101], v[84:85], v[112:113]
	v_pk_mul_f32 v[74:75], v[88:89], v[74:75]
	v_pk_fma_f32 v[76:77], v[104:105], v[76:77], v[78:79]
	v_cvt_pk_bf16_f32 v74, v74, v75
	v_pk_fma_f32 v[76:77], v[80:81], v[108:109], v[76:77]
	s_nop 0
	v_mul_f32_e32 v78, 0xbfb8aa3b, v76
	v_mul_f32_e32 v79, 0xbfb8aa3b, v77
	v_exp_f32_e32 v78, v78
	v_exp_f32_e32 v79, v79
	s_nop 0
	v_pk_add_f32 v[78:79], v[78:79], 1.0 op_sel_hi:[1,0]
	s_nop 0
	s_nop 0
	v_rcp_f32_e32 v80, v79
	s_nop 0
	v_mul_f32_e32 v77, v77, v80
	s_nop 0
	v_rcp_f32_e32 v79, v78
	s_nop 0
	v_mul_f32_e32 v76, v76, v79
	v_pk_mul_f32 v[76:77], v[86:87], v[76:77]
	s_nop 0
	v_cvt_pk_bf16_f32 v75, v76, v77
	v_mov_b64_e32 v[76:77], s[86:87]
	v_mad_i64_i32 v[76:77], s[54:55], v130, s53, v[76:77]
	v_lshl_add_u64 v[76:77], v[146:147], 1, v[76:77]
	global_store_dwordx2 v[76:77], v[74:75], off offset:32
	s_or_b64 exec, exec, s[2:3]
	s_and_saveexec_b64 s[2:3], s[4:5]
	s_cbranch_execnz .LBB0_48
	s_branch .LBB0_49

; DI void phase_ffnup(const Params& p, int layer, unsigned char* smem) {
;     ...
;       for (int mi = 0; mi < 4; ++mi) {
;         const int r = r0 + mi * 16;
;         if (r >= 2 && tt[mi] < TP) {
;           const float4 g1 = *(const float4*)(G + (r - 1) * 132 + gc);
;           const float4 g2 = *(const float4*)(G + (r - 2) * 132 + gc);
;           float cv[4];
;           cv[0] = c4.x + w0.x * g2.x + w1.x * g1.x + w2.x * acc[2 * n2][mi][0];
;           cv[1] = c4.y + w0.y * g2.y + w1.y * g1.y + w2.y * acc[2 * n2][mi][1];
;           cv[2] = c4.z + w0.z * g2.z + w1.z * g1.z + w2.z * acc[2 * n2][mi][2];
;           cv[3] = c4.w + w0.w * g2.w + w1.w * g1.w + w2.w * acc[2 * n2][mi][3];
;           float a[4];
; #pragma unroll
;           for (int e = 0; e < 4; ++e) a[e] = cv[e] / (1.f + __expf(-cv[e])) * acc[2 * n2 + 1][mi][e];
;           u32x2 pk = {pack2bf(a[0], a[1]), pack2bf(a[2], a[3])};
;           *(u32x2*)(p.act + (size_t)(b * TP + tt[mi]) * DFF + ff) = pk;
.LBB0_46:
	v_mov_b32_e32 v90, v152
	v_mov_b32_e32 v91, v152
	v_pk_mul_f32 v[96:97], v[82:83], v[152:153]
	v_lshl_add_u32 v82, v114, 2, v165
	v_pk_mul_f32 v[94:95], v[84:85], v[90:91]
	v_add_u32_e32 v83, 0xfffffdf0, v82
	v_add_u32_e32 v90, 0xfffffbe0, v82
	ds_read_b128 v[82:85], v83
	ds_read_b128 v[90:93], v90
	s_movk_i32 s53, 0x1600
	s_waitcnt vmcnt(0) lgkmcnt(0)
	v_pk_fma_f32 v[90:91], v[98:99], v[90:91], v[110:111]
	s_nop 0
	v_pk_fma_f32 v[82:83], v[102:103], v[82:83], v[90:91]
	s_nop 0
	v_pk_fma_f32 v[82:83], v[86:87], v[106:107], v[82:83]
	s_nop 0
	v_mul_f32_e32 v86, 0xbfb8aa3b, v82
	v_mul_f32_e32 v87, 0xbfb8aa3b, v83
	v_exp_f32_e32 v86, v86
	v_exp_f32_e32 v87, v87
	s_nop 0
	v_pk_add_f32 v[86:87], v[86:87], 1.0 op_sel_hi:[1,0]
	s_nop 0
	s_nop 0
	v_rcp_f32_e32 v90, v87
	s_nop 0
	v_mul_f32_e32 v83, v83, v90
	s_nop 0
	v_rcp_f32_e32 v87, v86
	s_nop 0
	v_mul_f32_e32 v82, v82, v87
	v_pk_fma_f32 v[86:87], v[100:101], v[92:93], v[112:113]
	v_pk_mul_f32 v[82:83], v[96:97], v[82:83]
	v_pk_fma_f32 v[84:85], v[104:105], v[84:85], v[86:87]
	v_cvt_pk_bf16_f32 v82, v82, v83
	v_pk_fma_f32 v[84:85], v[88:89], v[108:109], v[84:85]
	s_nop 0
	v_mul_f32_e32 v86, 0xbfb8aa3b, v84
	v_mul_f32_e32 v87, 0xbfb8aa3b, v85
	v_exp_f32_e32 v86, v86
	v_exp_f32_e32 v87, v87
	s_nop 0
	v_pk_add_f32 v[86:87], v[86:87], 1.0 op_sel_hi:[1,0]
	s_nop 0
	s_nop 0
	v_rcp_f32_e32 v88, v87
	s_nop 0
	v_mul_f32_e32 v85, v85, v88
	s_nop 0
	v_rcp_f32_e32 v87, v86
	s_nop 0
	v_mul_f32_e32 v84, v84, v87
	v_pk_mul_f32 v[84:85], v[94:95], v[84:85]
	s_nop 0
	v_cvt_pk_bf16_f32 v83, v84, v85
	v_mov_b64_e32 v[84:85], s[86:87]
	v_mad_i64_i32 v[84:85], s[54:55], v138, s53, v[84:85]
	v_lshl_add_u64 v[84:85], v[146:147], 1, v[84:85]
	global_store_dwordx2 v[84:85], v[82:83], off offset:32
	s_or_b64 exec, exec, s[2:3]
	s_and_saveexec_b64 s[2:3], s[50:51]
	s_cbranch_execnz .LBB0_44

; DI void phase_ffnup(const Params& p, int layer, unsigned char* smem) {
;     ...
; #pragma unroll
;     for (int n2 = 0; n2 < 4; ++n2) {
;       const int gc = gc0 + 16 * n2;
;       const int ff = 128 * nt + gc;
;       const float4 w0 = *(const float4*)(cw + ff), w1 = *(const float4*)(cw + DFF + ff), w2 = *(const float4*)(cw + 2 * DFF + ff);
;       const float4 c4 = *(const float4*)(cb + ff);
; #pragma unroll
;       for (int mi = 0; mi < 4; ++mi) {
;         const int r = r0 + mi * 16;
;         if (r >= 2 && tt[mi] < TP) {
;           const float4 g1 = *(const float4*)(G + (r - 1) * 132 + gc);
;           const float4 g2 = *(const float4*)(G + (r - 2) * 132 + gc);
;           float cv[4];
;           cv[0] = c4.x + w0.x * g2.x + w1.x * g1.x + w2.x * acc[2 * n2][mi][0];
;           cv[1] = c4.y + w0.y * g2.y + w1.y * g1.y + w2.y * acc[2 * n2][mi][1];
;           cv[2] = c4.z + w0.z * g2.z + w1.z * g1.z + w2.z * acc[2 * n2][mi][2];
;           cv[3] = c4.w + w0.w * g2.w + w1.w * g1.w + w2.w * acc[2 * n2][mi][3];
;           float a[4];
; #pragma unroll
;           for (int e = 0; e < 4; ++e) a[e] = cv[e] / (1.f + __expf(-cv[e])) * acc[2 * n2 + 1][mi][e];
;           u32x2 pk = {pack2bf(a[0], a[1]), pack2bf(a[2], a[3])};
;           *(u32x2*)(p.act + (size_t)(b * TP + tt[mi]) * DFF + ff) = pk;
.LBB0_48:
	v_mov_b32_e32 v74, v148
	v_mov_b32_e32 v75, v148
	v_pk_mul_f32 v[80:81], v[66:67], v[148:149]
	v_lshl_add_u32 v66, v114, 2, v161
	v_pk_mul_f32 v[78:79], v[68:69], v[74:75]
	v_add_u32_e32 v67, 0xfffffdf0, v66
	v_add_u32_e32 v74, 0xfffffbe0, v66
	ds_read_b128 v[66:69], v67
	ds_read_b128 v[74:77], v74
	s_movk_i32 s53, 0x1600
	s_waitcnt vmcnt(0) lgkmcnt(0)
	v_pk_fma_f32 v[74:75], v[98:99], v[74:75], v[110:111]
	s_nop 0
	v_pk_fma_f32 v[66:67], v[102:103], v[66:67], v[74:75]
	s_nop 0
	v_pk_fma_f32 v[66:67], v[70:71], v[106:107], v[66:67]
	s_nop 0
	v_mul_f32_e32 v70, 0xbfb8aa3b, v66
	v_mul_f32_e32 v71, 0xbfb8aa3b, v67
	v_exp_f32_e32 v70, v70
	v_exp_f32_e32 v71, v71
	s_nop 0
	v_pk_add_f32 v[70:71], v[70:71], 1.0 op_sel_hi:[1,0]
	s_nop 0
	s_nop 0
	v_rcp_f32_e32 v74, v71
	s_nop 0
	v_mul_f32_e32 v67, v67, v74
	s_nop 0
	v_rcp_f32_e32 v71, v70
	s_nop 0
	v_mul_f32_e32 v66, v66, v71
	v_pk_fma_f32 v[70:71], v[100:101], v[76:77], v[112:113]
	v_pk_mul_f32 v[66:67], v[80:81], v[66:67]
	v_pk_fma_f32 v[68:69], v[104:105], v[68:69], v[70:71]
	v_cvt_pk_bf16_f32 v66, v66, v67
	v_pk_fma_f32 v[68:69], v[72:73], v[108:109], v[68:69]
	s_nop 0
	v_mul_f32_e32 v70, 0xbfb8aa3b, v68
	v_mul_f32_e32 v71, 0xbfb8aa3b, v69
	v_exp_f32_e32 v70, v70
	v_exp_f32_e32 v71, v71
	s_nop 0
	v_pk_add_f32 v[70:71], v[70:71], 1.0 op_sel_hi:[1,0]
	s_nop 0
	s_nop 0
	v_rcp_f32_e32 v72, v71
	s_nop 0
	v_mul_f32_e32 v69, v69, v72
	s_nop 0
	v_rcp_f32_e32 v71, v70
	s_nop 0
	v_mul_f32_e32 v68, v68, v71
	v_pk_mul_f32 v[68:69], v[78:79], v[68:69]
	s_nop 0
	v_cvt_pk_bf16_f32 v67, v68, v69
	v_mov_b64_e32 v[68:69], s[86:87]
	v_mad_i64_i32 v[68:69], s[54:55], v126, s53, v[68:69]
	v_lshl_add_u64 v[68:69], v[146:147], 1, v[68:69]
	global_store_dwordx2 v[68:69], v[66:67], off offset:32
.LBB0_49:
	s_or_b64 exec, exec, s[2:3]
	v_add_u32_e32 v82, 32, v168
	v_add_u32_e32 v66, s52, v82
	v_ashrrev_i32_e32 v67, 31, v66
	v_lshlrev_b64 v[66:67], 2, v[66:67]
	v_lshl_add_u64 v[70:71], s[44:45], 0, v[66:67]
	v_lshl_add_u64 v[74:75], s[46:47], 0, v[66:67]
	global_load_dwordx4 v[66:69], v[158:159], off offset:128
	s_nop 0
	global_load_dwordx4 v[70:73], v[70:71], off
	s_nop 0
	global_load_dwordx4 v[74:77], v[74:75], off
	s_nop 0
	global_load_dwordx4 v[78:81], v[156:157], off offset:128
	s_and_saveexec_b64 s[2:3], s[34:35]
	s_cbranch_execz .LBB0_53
	v_pk_mul_f32 v[90:91], v[62:63], v[154:155]
	v_lshl_add_u32 v62, v82, 2, v169
	v_mov_b32_e32 v84, v154
	v_mov_b32_e32 v85, v154
	v_add_u32_e32 v63, 0xfffffdf0, v62
	v_pk_mul_f32 v[88:89], v[64:65], v[84:85]
	v_add_u32_e32 v83, 0xfffffbe0, v62
	ds_read_b128 v[62:65], v63
	ds_read_b128 v[84:87], v83
	s_movk_i32 s53, 0x1600
	s_waitcnt vmcnt(0) lgkmcnt(0)
	v_pk_fma_f32 v[84:85], v[66:67], v[84:85], v[78:79]
	s_nop 0
	v_pk_fma_f32 v[62:63], v[70:71], v[62:63], v[84:85]
	s_nop 0
	v_pk_fma_f32 v[58:59], v[58:59], v[74:75], v[62:63]
	s_nop 0
	v_mul_f32_e32 v62, 0xbfb8aa3b, v58
	v_mul_f32_e32 v63, 0xbfb8aa3b, v59
	v_exp_f32_e32 v62, v62
	v_exp_f32_e32 v63, v63
	s_nop 0
	v_pk_add_f32 v[62:63], v[62:63], 1.0 op_sel_hi:[1,0]
	s_nop 0
	s_nop 0
	v_rcp_f32_e32 v83, v63
	s_nop 0
	v_mul_f32_e32 v59, v59, v83
	s_nop 0
	v_rcp_f32_e32 v63, v62
	s_nop 0
	v_mul_f32_e32 v58, v58, v63
	v_pk_fma_f32 v[62:63], v[68:69], v[86:87], v[80:81]
	v_pk_mul_f32 v[58:59], v[90:91], v[58:59]
	v_pk_fma_f32 v[62:63], v[72:73], v[64:65], v[62:63]
	v_cvt_pk_bf16_f32 v58, v58, v59
	v_pk_fma_f32 v[60:61], v[60:61], v[76:77], v[62:63]
	s_nop 0
	v_mul_f32_e32 v62, 0xbfb8aa3b, v60
	v_mul_f32_e32 v63, 0xbfb8aa3b, v61
	v_exp_f32_e32 v62, v62
	v_exp_f32_e32 v63, v63
	s_nop 0
	v_pk_add_f32 v[62:63], v[62:63], 1.0 op_sel_hi:[1,0]
	s_nop 0
	s_nop 0
	v_rcp_f32_e32 v64, v63
	s_nop 0
	v_mul_f32_e32 v61, v61, v64
	s_nop 0
	v_rcp_f32_e32 v63, v62
	s_nop 0
	v_mul_f32_e32 v60, v60, v63
	v_pk_mul_f32 v[60:61], v[88:89], v[60:61]
	s_nop 0
	v_cvt_pk_bf16_f32 v59, v60, v61
	v_mov_b64_e32 v[60:61], s[86:87]
	v_mad_i64_i32 v[60:61], s[54:55], v162, s53, v[60:61]
	v_lshl_add_u64 v[60:61], v[146:147], 1, v[60:61]
	global_store_dwordx2 v[60:61], v[58:59], off offset:64
	s_or_b64 exec, exec, s[2:3]
	s_and_saveexec_b64 s[2:3], s[48:49]
	s_cbranch_execnz .LBB0_54

; DI void phase_ffnup(const Params& p, int layer, unsigned char* smem) {
;     ...
;       for (int mi = 0; mi < 4; ++mi) {
;         const int r = r0 + mi * 16;
;         if (r >= 2 && tt[mi] < TP) {
;           const float4 g1 = *(const float4*)(G + (r - 1) * 132 + gc);
;           const float4 g2 = *(const float4*)(G + (r - 2) * 132 + gc);
;           float cv[4];
;           cv[0] = c4.x + w0.x * g2.x + w1.x * g1.x + w2.x * acc[2 * n2][mi][0];
;           cv[1] = c4.y + w0.y * g2.y + w1.y * g1.y + w2.y * acc[2 * n2][mi][1];
;           cv[2] = c4.z + w0.z * g2.z + w1.z * g1.z + w2.z * acc[2 * n2][mi][2];
;           cv[3] = c4.w + w0.w * g2.w + w1.w * g1.w + w2.w * acc[2 * n2][mi][3];
;           float a[4];
; #pragma unroll
;           for (int e = 0; e < 4; ++e) a[e] = cv[e] / (1.f + __expf(-cv[e])) * acc[2 * n2 + 1][mi][e];
;           u32x2 pk = {pack2bf(a[0], a[1]), pack2bf(a[2], a[3])};
;           *(u32x2*)(p.act + (size_t)(b * TP + tt[mi]) * DFF + ff) = pk;
.LBB0_52:
	v_mov_b32_e32 v50, v150
	v_mov_b32_e32 v51, v150
	v_pk_mul_f32 v[56:57], v[42:43], v[150:151]
	v_lshl_add_u32 v42, v82, 2, v164
	v_pk_mul_f32 v[54:55], v[44:45], v[50:51]
	v_add_u32_e32 v43, 0xfffffdf0, v42
	v_add_u32_e32 v50, 0xfffffbe0, v42
	ds_read_b128 v[42:45], v43
	ds_read_b128 v[50:53], v50
	s_movk_i32 s53, 0x1600
	s_waitcnt vmcnt(0) lgkmcnt(0)
	v_pk_fma_f32 v[50:51], v[66:67], v[50:51], v[78:79]
	s_nop 0
	v_pk_fma_f32 v[42:43], v[70:71], v[42:43], v[50:51]
	s_nop 0
	v_pk_fma_f32 v[42:43], v[46:47], v[74:75], v[42:43]
	s_nop 0
	v_mul_f32_e32 v46, 0xbfb8aa3b, v42
	v_mul_f32_e32 v47, 0xbfb8aa3b, v43
	v_exp_f32_e32 v46, v46
	v_exp_f32_e32 v47, v47
	s_nop 0
	v_pk_add_f32 v[46:47], v[46:47], 1.0 op_sel_hi:[1,0]
	s_nop 0
	s_nop 0
	v_rcp_f32_e32 v50, v47
	s_nop 0
	v_mul_f32_e32 v43, v43, v50
	s_nop 0
	v_rcp_f32_e32 v47, v46
	s_nop 0
	v_mul_f32_e32 v42, v42, v47
	v_pk_fma_f32 v[46:47], v[68:69], v[52:53], v[80:81]
	v_pk_mul_f32 v[42:43], v[56:57], v[42:43]
	v_pk_fma_f32 v[44:45], v[72:73], v[44:45], v[46:47]
	v_cvt_pk_bf16_f32 v42, v42, v43
	v_pk_fma_f32 v[44:45], v[48:49], v[76:77], v[44:45]
	s_nop 0
	v_mul_f32_e32 v46, 0xbfb8aa3b, v44
	v_mul_f32_e32 v47, 0xbfb8aa3b, v45
	v_exp_f32_e32 v46, v46
	v_exp_f32_e32 v47, v47
	s_nop 0
	v_pk_add_f32 v[46:47], v[46:47], 1.0 op_sel_hi:[1,0]
	s_nop 0
	s_nop 0
	v_rcp_f32_e32 v48, v47
	s_nop 0
	v_mul_f32_e32 v45, v45, v48
	s_nop 0
	v_rcp_f32_e32 v47, v46
	s_nop 0
	v_mul_f32_e32 v44, v44, v47
	v_pk_mul_f32 v[44:45], v[54:55], v[44:45]
	s_nop 0
	v_cvt_pk_bf16_f32 v43, v44, v45
	v_mov_b64_e32 v[44:45], s[86:87]
	v_mad_i64_i32 v[44:45], s[54:55], v130, s53, v[44:45]
	v_lshl_add_u64 v[44:45], v[146:147], 1, v[44:45]
	global_store_dwordx2 v[44:45], v[42:43], off offset:64
	s_or_b64 exec, exec, s[2:3]
	s_and_saveexec_b64 s[2:3], s[4:5]
	s_cbranch_execnz .LBB0_56
	s_branch .LBB0_57

; DI void phase_ffnup(const Params& p, int layer, unsigned char* smem) {
;     ...
;       for (int mi = 0; mi < 4; ++mi) {
;         const int r = r0 + mi * 16;
;         if (r >= 2 && tt[mi] < TP) {
;           const float4 g1 = *(const float4*)(G + (r - 1) * 132 + gc);
;           const float4 g2 = *(const float4*)(G + (r - 2) * 132 + gc);
;           float cv[4];
;           cv[0] = c4.x + w0.x * g2.x + w1.x * g1.x + w2.x * acc[2 * n2][mi][0];
;           cv[1] = c4.y + w0.y * g2.y + w1.y * g1.y + w2.y * acc[2 * n2][mi][1];
;           cv[2] = c4.z + w0.z * g2.z + w1.z * g1.z + w2.z * acc[2 * n2][mi][2];
;           cv[3] = c4.w + w0.w * g2.w + w1.w * g1.w + w2.w * acc[2 * n2][mi][3];
;           float a[4];
; #pragma unroll
;           for (int e = 0; e < 4; ++e) a[e] = cv[e] / (1.f + __expf(-cv[e])) * acc[2 * n2 + 1][mi][e];
;           u32x2 pk = {pack2bf(a[0], a[1]), pack2bf(a[2], a[3])};
;           *(u32x2*)(p.act + (size_t)(b * TP + tt[mi]) * DFF + ff) = pk;
.LBB0_54:
	v_mov_b32_e32 v58, v152
	v_mov_b32_e32 v59, v152
	v_pk_mul_f32 v[64:65], v[50:51], v[152:153]
	v_lshl_add_u32 v50, v82, 2, v165
	v_pk_mul_f32 v[62:63], v[52:53], v[58:59]
	v_add_u32_e32 v51, 0xfffffdf0, v50
	v_add_u32_e32 v58, 0xfffffbe0, v50
	ds_read_b128 v[50:53], v51
	ds_read_b128 v[58:61], v58
	s_movk_i32 s53, 0x1600
	s_waitcnt vmcnt(0) lgkmcnt(0)
	v_pk_fma_f32 v[58:59], v[66:67], v[58:59], v[78:79]
	s_nop 0
	v_pk_fma_f32 v[50:51], v[70:71], v[50:51], v[58:59]
	s_nop 0
	v_pk_fma_f32 v[50:51], v[54:55], v[74:75], v[50:51]
	s_nop 0
	v_mul_f32_e32 v54, 0xbfb8aa3b, v50
	v_mul_f32_e32 v55, 0xbfb8aa3b, v51
	v_exp_f32_e32 v54, v54
	v_exp_f32_e32 v55, v55
	s_nop 0
	v_pk_add_f32 v[54:55], v[54:55], 1.0 op_sel_hi:[1,0]
	s_nop 0
	s_nop 0
	v_rcp_f32_e32 v58, v55
	s_nop 0
	v_mul_f32_e32 v51, v51, v58
	s_nop 0
	v_rcp_f32_e32 v55, v54
	s_nop 0
	v_mul_f32_e32 v50, v50, v55
	v_pk_fma_f32 v[54:55], v[68:69], v[60:61], v[80:81]
	v_pk_mul_f32 v[50:51], v[64:65], v[50:51]
	v_pk_fma_f32 v[52:53], v[72:73], v[52:53], v[54:55]
	v_cvt_pk_bf16_f32 v50, v50, v51
	v_pk_fma_f32 v[52:53], v[56:57], v[76:77], v[52:53]
	s_nop 0
	v_mul_f32_e32 v54, 0xbfb8aa3b, v52
	v_mul_f32_e32 v55, 0xbfb8aa3b, v53
	v_exp_f32_e32 v54, v54
	v_exp_f32_e32 v55, v55
	s_nop 0
	v_pk_add_f32 v[54:55], v[54:55], 1.0 op_sel_hi:[1,0]
	s_nop 0
	s_nop 0
	v_rcp_f32_e32 v56, v55
	s_nop 0
	v_mul_f32_e32 v53, v53, v56
	s_nop 0
	v_rcp_f32_e32 v55, v54
	s_nop 0
	v_mul_f32_e32 v52, v52, v55
	v_pk_mul_f32 v[52:53], v[62:63], v[52:53]
	s_nop 0
	v_cvt_pk_bf16_f32 v51, v52, v53
	v_mov_b64_e32 v[52:53], s[86:87]
	v_mad_i64_i32 v[52:53], s[54:55], v138, s53, v[52:53]
	v_lshl_add_u64 v[52:53], v[146:147], 1, v[52:53]
	global_store_dwordx2 v[52:53], v[50:51], off offset:64
	s_or_b64 exec, exec, s[2:3]
	s_and_saveexec_b64 s[2:3], s[50:51]
	s_cbranch_execnz .LBB0_52

; DI void phase_ffnup(const Params& p, int layer, unsigned char* smem) {
;     ...
; #pragma unroll
;     for (int n2 = 0; n2 < 4; ++n2) {
;       const int gc = gc0 + 16 * n2;
;       const int ff = 128 * nt + gc;
;       const float4 w0 = *(const float4*)(cw + ff), w1 = *(const float4*)(cw + DFF + ff), w2 = *(const float4*)(cw + 2 * DFF + ff);
;       const float4 c4 = *(const float4*)(cb + ff);
; #pragma unroll
;       for (int mi = 0; mi < 4; ++mi) {
;         const int r = r0 + mi * 16;
;         if (r >= 2 && tt[mi] < TP) {
;           const float4 g1 = *(const float4*)(G + (r - 1) * 132 + gc);
;           const float4 g2 = *(const float4*)(G + (r - 2) * 132 + gc);
;           float cv[4];
;           cv[0] = c4.x + w0.x * g2.x + w1.x * g1.x + w2.x * acc[2 * n2][mi][0];
;           cv[1] = c4.y + w0.y * g2.y + w1.y * g1.y + w2.y * acc[2 * n2][mi][1];
;           cv[2] = c4.z + w0.z * g2.z + w1.z * g1.z + w2.z * acc[2 * n2][mi][2];
;           cv[3] = c4.w + w0.w * g2.w + w1.w * g1.w + w2.w * acc[2 * n2][mi][3];
;           float a[4];
; #pragma unroll
;           for (int e = 0; e < 4; ++e) a[e] = cv[e] / (1.f + __expf(-cv[e])) * acc[2 * n2 + 1][mi][e];
;           u32x2 pk = {pack2bf(a[0], a[1]), pack2bf(a[2], a[3])};
;           *(u32x2*)(p.act + (size_t)(b * TP + tt[mi]) * DFF + ff) = pk;
.LBB0_56:
	v_mov_b32_e32 v42, v148
	v_mov_b32_e32 v43, v148
	v_pk_mul_f32 v[48:49], v[34:35], v[148:149]
	v_lshl_add_u32 v34, v82, 2, v161
	v_pk_mul_f32 v[46:47], v[36:37], v[42:43]
	v_add_u32_e32 v35, 0xfffffdf0, v34
	v_add_u32_e32 v42, 0xfffffbe0, v34
	ds_read_b128 v[34:37], v35
	ds_read_b128 v[42:45], v42
	s_movk_i32 s53, 0x1600
	s_waitcnt vmcnt(0) lgkmcnt(0)
	v_pk_fma_f32 v[42:43], v[66:67], v[42:43], v[78:79]
	s_nop 0
	v_pk_fma_f32 v[34:35], v[70:71], v[34:35], v[42:43]
	s_nop 0
	v_pk_fma_f32 v[34:35], v[38:39], v[74:75], v[34:35]
	s_nop 0
	v_mul_f32_e32 v38, 0xbfb8aa3b, v34
	v_mul_f32_e32 v39, 0xbfb8aa3b, v35
	v_exp_f32_e32 v38, v38
	v_exp_f32_e32 v39, v39
	s_nop 0
	v_pk_add_f32 v[38:39], v[38:39], 1.0 op_sel_hi:[1,0]
	s_nop 0
	s_nop 0
	v_rcp_f32_e32 v42, v39
	s_nop 0
	v_mul_f32_e32 v35, v35, v42
	s_nop 0
	v_rcp_f32_e32 v39, v38
	s_nop 0
	v_mul_f32_e32 v34, v34, v39
	v_pk_fma_f32 v[38:39], v[68:69], v[44:45], v[80:81]
	v_pk_mul_f32 v[34:35], v[48:49], v[34:35]
	v_pk_fma_f32 v[36:37], v[72:73], v[36:37], v[38:39]
	v_cvt_pk_bf16_f32 v34, v34, v35
	v_pk_fma_f32 v[36:37], v[40:41], v[76:77], v[36:37]
	s_nop 0
	v_mul_f32_e32 v38, 0xbfb8aa3b, v36
	v_mul_f32_e32 v39, 0xbfb8aa3b, v37
	v_exp_f32_e32 v38, v38
	v_exp_f32_e32 v39, v39
	s_nop 0
	v_pk_add_f32 v[38:39], v[38:39], 1.0 op_sel_hi:[1,0]
	s_nop 0
	s_nop 0
	v_rcp_f32_e32 v40, v39
	s_nop 0
	v_mul_f32_e32 v37, v37, v40
	s_nop 0
	v_rcp_f32_e32 v39, v38
	s_nop 0
	v_mul_f32_e32 v36, v36, v39
	v_pk_mul_f32 v[36:37], v[46:47], v[36:37]
	s_nop 0
	v_cvt_pk_bf16_f32 v35, v36, v37
	v_mov_b64_e32 v[36:37], s[86:87]
	v_mad_i64_i32 v[36:37], s[54:55], v126, s53, v[36:37]
	v_lshl_add_u64 v[36:37], v[146:147], 1, v[36:37]
	global_store_dwordx2 v[36:37], v[34:35], off offset:64
.LBB0_57:
	s_or_b64 exec, exec, s[2:3]
	v_add_u32_e32 v50, 48, v168
	v_add_u32_e32 v34, s52, v50
	v_ashrrev_i32_e32 v35, 31, v34
	v_lshlrev_b64 v[34:35], 2, v[34:35]
	v_lshl_add_u64 v[38:39], s[44:45], 0, v[34:35]
	v_lshl_add_u64 v[42:43], s[46:47], 0, v[34:35]
	global_load_dwordx4 v[34:37], v[158:159], off offset:192
	s_nop 0
	global_load_dwordx4 v[38:41], v[38:39], off
	s_nop 0
	global_load_dwordx4 v[42:45], v[42:43], off
	s_nop 0
	global_load_dwordx4 v[46:49], v[156:157], off offset:192
	s_and_saveexec_b64 s[2:3], s[34:35]
	s_cbranch_execz .LBB0_61
	v_pk_mul_f32 v[58:59], v[30:31], v[154:155]
	v_lshl_add_u32 v30, v50, 2, v169
	v_mov_b32_e32 v52, v154
	v_mov_b32_e32 v53, v154
	v_add_u32_e32 v31, 0xfffffdf0, v30
	v_pk_mul_f32 v[56:57], v[32:33], v[52:53]
	v_add_u32_e32 v51, 0xfffffbe0, v30
	ds_read_b128 v[30:33], v31
	ds_read_b128 v[52:55], v51
	s_waitcnt vmcnt(0) lgkmcnt(0)
	v_pk_fma_f32 v[52:53], v[34:35], v[52:53], v[46:47]
	s_nop 0
	v_pk_fma_f32 v[30:31], v[38:39], v[30:31], v[52:53]
	s_nop 0
	v_pk_fma_f32 v[26:27], v[26:27], v[42:43], v[30:31]
	s_nop 0
	v_mul_f32_e32 v30, 0xbfb8aa3b, v26
	v_mul_f32_e32 v31, 0xbfb8aa3b, v27
	v_exp_f32_e32 v30, v30
	v_exp_f32_e32 v31, v31
	s_nop 0
	v_pk_add_f32 v[30:31], v[30:31], 1.0 op_sel_hi:[1,0]
	s_nop 0
	s_nop 0
	v_rcp_f32_e32 v51, v31
	s_nop 0
	v_mul_f32_e32 v27, v27, v51
	s_nop 0
	v_rcp_f32_e32 v31, v30
	s_nop 0
	v_mul_f32_e32 v26, v26, v31
	v_pk_fma_f32 v[30:31], v[36:37], v[54:55], v[48:49]
	v_pk_mul_f32 v[26:27], v[58:59], v[26:27]
	v_pk_fma_f32 v[30:31], v[40:41], v[32:33], v[30:31]
	v_cvt_pk_bf16_f32 v26, v26, v27
	v_pk_fma_f32 v[28:29], v[28:29], v[44:45], v[30:31]
	s_nop 0
	v_mul_f32_e32 v30, 0xbfb8aa3b, v28
	v_mul_f32_e32 v31, 0xbfb8aa3b, v29
	v_exp_f32_e32 v30, v30
	v_exp_f32_e32 v31, v31
	s_nop 0
	v_pk_add_f32 v[30:31], v[30:31], 1.0 op_sel_hi:[1,0]
	s_nop 0
	s_nop 0
	v_rcp_f32_e32 v32, v31
	s_nop 0
	v_mul_f32_e32 v29, v29, v32
	s_movk_i32 s34, 0x1600
	v_rcp_f32_e32 v31, v30
	s_nop 0
	v_mul_f32_e32 v28, v28, v31
	v_pk_mul_f32 v[28:29], v[56:57], v[28:29]
	s_nop 0
	v_cvt_pk_bf16_f32 v27, v28, v29
	v_mov_b64_e32 v[28:29], s[86:87]
	v_mad_i64_i32 v[28:29], s[34:35], v162, s34, v[28:29]
	v_lshl_add_u64 v[28:29], v[146:147], 1, v[28:29]
	global_store_dwordx2 v[28:29], v[26:27], off offset:96
	s_or_b64 exec, exec, s[2:3]
	s_and_saveexec_b64 s[2:3], s[48:49]
	s_cbranch_execnz .LBB0_62

; DI void phase_ffnup(const Params& p, int layer, unsigned char* smem) {
;     ...
;       for (int mi = 0; mi < 4; ++mi) {
;         const int r = r0 + mi * 16;
;         if (r >= 2 && tt[mi] < TP) {
;           const float4 g1 = *(const float4*)(G + (r - 1) * 132 + gc);
;           const float4 g2 = *(const float4*)(G + (r - 2) * 132 + gc);
;           float cv[4];
;           cv[0] = c4.x + w0.x * g2.x + w1.x * g1.x + w2.x * acc[2 * n2][mi][0];
;           cv[1] = c4.y + w0.y * g2.y + w1.y * g1.y + w2.y * acc[2 * n2][mi][1];
;           cv[2] = c4.z + w0.z * g2.z + w1.z * g1.z + w2.z * acc[2 * n2][mi][2];
;           cv[3] = c4.w + w0.w * g2.w + w1.w * g1.w + w2.w * acc[2 * n2][mi][3];
;           float a[4];
; #pragma unroll
;           for (int e = 0; e < 4; ++e) a[e] = cv[e] / (1.f + __expf(-cv[e])) * acc[2 * n2 + 1][mi][e];
;           u32x2 pk = {pack2bf(a[0], a[1]), pack2bf(a[2], a[3])};
;           *(u32x2*)(p.act + (size_t)(b * TP + tt[mi]) * DFF + ff) = pk;
.LBB0_60:
	v_mov_b32_e32 v18, v150
	v_mov_b32_e32 v19, v150
	v_pk_mul_f32 v[24:25], v[10:11], v[150:151]
	v_lshl_add_u32 v10, v50, 2, v164
	v_pk_mul_f32 v[22:23], v[12:13], v[18:19]
	v_add_u32_e32 v11, 0xfffffdf0, v10
	v_add_u32_e32 v18, 0xfffffbe0, v10
	ds_read_b128 v[10:13], v11
	ds_read_b128 v[18:21], v18
	s_waitcnt vmcnt(0) lgkmcnt(0)
	v_pk_fma_f32 v[18:19], v[34:35], v[18:19], v[46:47]
	s_nop 0
	v_pk_fma_f32 v[10:11], v[38:39], v[10:11], v[18:19]
	s_nop 0
	v_pk_fma_f32 v[10:11], v[14:15], v[42:43], v[10:11]
	s_nop 0
	v_mul_f32_e32 v14, 0xbfb8aa3b, v10
	v_mul_f32_e32 v15, 0xbfb8aa3b, v11
	v_exp_f32_e32 v14, v14
	v_exp_f32_e32 v15, v15
	s_nop 0
	v_pk_add_f32 v[14:15], v[14:15], 1.0 op_sel_hi:[1,0]
	s_nop 0
	s_nop 0
	v_rcp_f32_e32 v18, v15
	s_nop 0
	v_mul_f32_e32 v11, v11, v18
	s_nop 0
	v_rcp_f32_e32 v15, v14
	s_nop 0
	v_mul_f32_e32 v10, v10, v15
	v_pk_fma_f32 v[14:15], v[36:37], v[20:21], v[48:49]
	v_pk_mul_f32 v[10:11], v[24:25], v[10:11]
	v_pk_fma_f32 v[12:13], v[40:41], v[12:13], v[14:15]
	v_cvt_pk_bf16_f32 v10, v10, v11
	v_pk_fma_f32 v[12:13], v[16:17], v[44:45], v[12:13]
	s_nop 0
	v_mul_f32_e32 v14, 0xbfb8aa3b, v12
	v_mul_f32_e32 v15, 0xbfb8aa3b, v13
	v_exp_f32_e32 v14, v14
	v_exp_f32_e32 v15, v15
	s_nop 0
	v_pk_add_f32 v[14:15], v[14:15], 1.0 op_sel_hi:[1,0]
	s_nop 0
	s_nop 0
	v_rcp_f32_e32 v16, v15
	s_nop 0
	v_mul_f32_e32 v13, v13, v16
	s_movk_i32 s34, 0x1600
	v_rcp_f32_e32 v15, v14
	s_nop 0
	v_mul_f32_e32 v12, v12, v15
	v_pk_mul_f32 v[12:13], v[22:23], v[12:13]
	s_nop 0
	v_cvt_pk_bf16_f32 v11, v12, v13
	v_mov_b64_e32 v[12:13], s[86:87]
	v_mad_i64_i32 v[12:13], s[34:35], v130, s34, v[12:13]
	v_lshl_add_u64 v[12:13], v[146:147], 1, v[12:13]
	global_store_dwordx2 v[12:13], v[10:11], off offset:96
	s_or_b64 exec, exec, s[2:3]
	s_and_saveexec_b64 s[2:3], s[4:5]
	s_cbranch_execz .LBB0_22
	s_branch .LBB0_64

; DI void phase_ffnup(const Params& p, int layer, unsigned char* smem) {
;     ...
;       for (int mi = 0; mi < 4; ++mi) {
;         const int r = r0 + mi * 16;
;         if (r >= 2 && tt[mi] < TP) {
;           const float4 g1 = *(const float4*)(G + (r - 1) * 132 + gc);
;           const float4 g2 = *(const float4*)(G + (r - 2) * 132 + gc);
;           float cv[4];
;           cv[0] = c4.x + w0.x * g2.x + w1.x * g1.x + w2.x * acc[2 * n2][mi][0];
;           cv[1] = c4.y + w0.y * g2.y + w1.y * g1.y + w2.y * acc[2 * n2][mi][1];
;           cv[2] = c4.z + w0.z * g2.z + w1.z * g1.z + w2.z * acc[2 * n2][mi][2];
;           cv[3] = c4.w + w0.w * g2.w + w1.w * g1.w + w2.w * acc[2 * n2][mi][3];
;           float a[4];
; #pragma unroll
;           for (int e = 0; e < 4; ++e) a[e] = cv[e] / (1.f + __expf(-cv[e])) * acc[2 * n2 + 1][mi][e];
;           u32x2 pk = {pack2bf(a[0], a[1]), pack2bf(a[2], a[3])};
;           *(u32x2*)(p.act + (size_t)(b * TP + tt[mi]) * DFF + ff) = pk;
.LBB0_62:
	v_mov_b32_e32 v26, v152
	v_mov_b32_e32 v27, v152
	v_pk_mul_f32 v[32:33], v[22:23], v[152:153]
	v_lshl_add_u32 v22, v50, 2, v165
	v_pk_mul_f32 v[30:31], v[24:25], v[26:27]
	v_add_u32_e32 v23, 0xfffffdf0, v22
	v_add_u32_e32 v26, 0xfffffbe0, v22
	ds_read_b128 v[22:25], v23
	ds_read_b128 v[26:29], v26
	s_waitcnt vmcnt(0) lgkmcnt(0)
	v_pk_fma_f32 v[26:27], v[34:35], v[26:27], v[46:47]
	s_nop 0
	v_pk_fma_f32 v[22:23], v[38:39], v[22:23], v[26:27]
	s_nop 0
	v_pk_fma_f32 v[18:19], v[18:19], v[42:43], v[22:23]
	s_nop 0
	v_mul_f32_e32 v22, 0xbfb8aa3b, v18
	v_mul_f32_e32 v23, 0xbfb8aa3b, v19
	v_exp_f32_e32 v22, v22
	v_exp_f32_e32 v23, v23
	s_nop 0
	v_pk_add_f32 v[22:23], v[22:23], 1.0 op_sel_hi:[1,0]
	s_nop 0
	s_nop 0
	v_rcp_f32_e32 v26, v23
	s_nop 0
	v_mul_f32_e32 v19, v19, v26
	s_nop 0
	v_rcp_f32_e32 v23, v22
	s_nop 0
	v_mul_f32_e32 v18, v18, v23
	v_pk_fma_f32 v[22:23], v[36:37], v[28:29], v[48:49]
	v_pk_mul_f32 v[18:19], v[32:33], v[18:19]
	v_pk_fma_f32 v[22:23], v[40:41], v[24:25], v[22:23]
	v_cvt_pk_bf16_f32 v18, v18, v19
	v_pk_fma_f32 v[20:21], v[20:21], v[44:45], v[22:23]
	s_nop 0
	v_mul_f32_e32 v22, 0xbfb8aa3b, v20
	v_mul_f32_e32 v23, 0xbfb8aa3b, v21
	v_exp_f32_e32 v22, v22
	v_exp_f32_e32 v23, v23
	s_nop 0
	v_pk_add_f32 v[22:23], v[22:23], 1.0 op_sel_hi:[1,0]
	s_nop 0
	s_nop 0
	v_rcp_f32_e32 v24, v23
	s_nop 0
	v_mul_f32_e32 v21, v21, v24
	s_movk_i32 s34, 0x1600
	v_rcp_f32_e32 v23, v22
	s_nop 0
	v_mul_f32_e32 v20, v20, v23
	v_pk_mul_f32 v[20:21], v[30:31], v[20:21]
	s_nop 0
	v_cvt_pk_bf16_f32 v19, v20, v21
	v_mov_b64_e32 v[20:21], s[86:87]
	v_mad_i64_i32 v[20:21], s[34:35], v138, s34, v[20:21]
	v_lshl_add_u64 v[20:21], v[146:147], 1, v[20:21]
	global_store_dwordx2 v[20:21], v[18:19], off offset:96
	s_or_b64 exec, exec, s[2:3]
	s_and_saveexec_b64 s[2:3], s[50:51]
	s_cbranch_execnz .LBB0_60

; DI void phase_ffnup(const Params& p, int layer, unsigned char* smem) {
;     ...
;       for (int mi = 0; mi < 4; ++mi) {
;         const int r = r0 + mi * 16;
;         if (r >= 2 && tt[mi] < TP) {
;           const float4 g1 = *(const float4*)(G + (r - 1) * 132 + gc);
;           const float4 g2 = *(const float4*)(G + (r - 2) * 132 + gc);
;           float cv[4];
;           cv[0] = c4.x + w0.x * g2.x + w1.x * g1.x + w2.x * acc[2 * n2][mi][0];
;           cv[1] = c4.y + w0.y * g2.y + w1.y * g1.y + w2.y * acc[2 * n2][mi][1];
;           cv[2] = c4.z + w0.z * g2.z + w1.z * g1.z + w2.z * acc[2 * n2][mi][2];
;           cv[3] = c4.w + w0.w * g2.w + w1.w * g1.w + w2.w * acc[2 * n2][mi][3];
;           float a[4];
; #pragma unroll
;           for (int e = 0; e < 4; ++e) a[e] = cv[e] / (1.f + __expf(-cv[e])) * acc[2 * n2 + 1][mi][e];
;           u32x2 pk = {pack2bf(a[0], a[1]), pack2bf(a[2], a[3])};
;           *(u32x2*)(p.act + (size_t)(b * TP + tt[mi]) * DFF + ff) = pk;
.LBB0_64:
	v_mov_b32_e32 v10, v148
	v_mov_b32_e32 v11, v148
	v_pk_mul_f32 v[16:17], v[2:3], v[148:149]
	v_lshl_add_u32 v2, v50, 2, v161
	v_pk_mul_f32 v[14:15], v[4:5], v[10:11]
	v_add_u32_e32 v3, 0xfffffdf0, v2
	v_add_u32_e32 v10, 0xfffffbe0, v2
	ds_read_b128 v[2:5], v3
	ds_read_b128 v[10:13], v10
	s_waitcnt vmcnt(0) lgkmcnt(0)
	v_pk_fma_f32 v[10:11], v[34:35], v[10:11], v[46:47]
	s_nop 0
	v_pk_fma_f32 v[2:3], v[38:39], v[2:3], v[10:11]
	s_nop 0
	v_pk_fma_f32 v[2:3], v[6:7], v[42:43], v[2:3]
	s_nop 0
	v_mul_f32_e32 v6, 0xbfb8aa3b, v2
	v_mul_f32_e32 v7, 0xbfb8aa3b, v3
	v_exp_f32_e32 v6, v6
	v_exp_f32_e32 v7, v7
	s_nop 0
	v_pk_add_f32 v[6:7], v[6:7], 1.0 op_sel_hi:[1,0]
	s_nop 0
	s_nop 0
	v_rcp_f32_e32 v10, v7
	s_nop 0
	v_mul_f32_e32 v3, v3, v10
	s_nop 0
	v_rcp_f32_e32 v7, v6
	s_nop 0
	v_mul_f32_e32 v2, v2, v7
	v_pk_fma_f32 v[6:7], v[36:37], v[12:13], v[48:49]
	v_pk_mul_f32 v[2:3], v[16:17], v[2:3]
	v_pk_fma_f32 v[4:5], v[40:41], v[4:5], v[6:7]
	v_cvt_pk_bf16_f32 v2, v2, v3
	v_pk_fma_f32 v[4:5], v[8:9], v[44:45], v[4:5]
	s_nop 0
	v_mul_f32_e32 v6, 0xbfb8aa3b, v4
	v_mul_f32_e32 v7, 0xbfb8aa3b, v5
	v_exp_f32_e32 v6, v6
	v_exp_f32_e32 v7, v7
	s_nop 0
	v_pk_add_f32 v[6:7], v[6:7], 1.0 op_sel_hi:[1,0]
	s_nop 0
	s_nop 0
	v_rcp_f32_e32 v8, v7
	s_nop 0
	v_mul_f32_e32 v5, v5, v8
	s_movk_i32 s4, 0x1600
	v_rcp_f32_e32 v7, v6
	s_nop 0
	v_mul_f32_e32 v4, v4, v7
	v_pk_mul_f32 v[4:5], v[14:15], v[4:5]
	s_nop 0
	v_cvt_pk_bf16_f32 v3, v4, v5
	v_mov_b64_e32 v[4:5], s[86:87]
	v_mad_i64_i32 v[4:5], s[4:5], v126, s4, v[4:5]
	v_lshl_add_u64 v[4:5], v[146:147], 1, v[4:5]
	global_store_dwordx2 v[4:5], v[2:3], off offset:96
	s_branch .LBB0_22

; DI f32x4 mfma16(bf16x8 a, bf16x8 b, f32x4 c) { return __builtin_amdgcn_mfma_f32_16x16x32_bf16(a, b, c, 0, 0, 0); }
; template <int MI, int NI>
; DI void gemm_kloop(const u16* Au, int lda, const u16* Bu, int ldb, int K, f32x4 (&acc)[NI][MI], unsigned char* smem) {
;     ...
;   for (int kt = 0; kt < nk; ++kt) {
;     __syncthreads();
;     if (kt + 1 < nk) {
;       SWRITE((kt + 1) & 1);
;       if (kt + 2 < nk) GLOAD((kt + 2) << 6);
;     }
;     {
;       const unsigned char* sa = smem + (kt & 1) * 65536;
;       const unsigned char* sb = sa + 32768;
; #pragma unroll
;       for (int ks = 0; ks < 2; ++ks) {
;         const int fo = ks ? fro1 : fro0;
;         bf16x8 af[MI];
; #pragma unroll
;         for (int i = 0; i < MI; ++i) af[i] = *(const bf16x8*)(sa + (wm * 16 * MI + i * 16) * 128 + fo);
; #pragma unroll
;         for (int nh = 0; nh < NI; nh += 4) {
;           bf16x8 wf[4];
; #pragma unroll
;           for (int i = 0; i < 4; ++i) wf[i] = *(const bf16x8*)(sb + (wn * 16 * NI + (nh + i) * 16) * 128 + fo);
; #pragma unroll
;           for (int ni = 0; ni < 4; ++ni)
; #pragma unroll
;             for (int mi = 0; mi < MI; ++mi) acc[nh + ni][mi] = mfma16(wf[ni], af[mi], acc[nh + ni][mi]);
;         }
; template <int MI>
; DI void merge_tile(const Params& p, int layer, int rowbase, int nt, unsigned char* smem) {
;     ...
;     u32 brp[4][MI][2];
; #pragma unroll
;     for (int ni = 0; ni < 4; ++ni)
; #pragma unroll
;       for (int mi = 0; mi < MI; ++mi) {
;         brp[ni][mi][0] = pack2bf(acc[ni][mi][0], acc[ni][mi][1]);
;         brp[ni][mi][1] = pack2bf(acc[ni][mi][2], acc[ni][mi][3]);
;       }
.Lk_mgate:
	s_waitcnt vmcnt(0) lgkmcnt(0)
	s_barrier
	ds_read_b128 v[130:133], v225 offset:32768
	ds_read_b128 v[150:153], v155
	ds_read_b128 v[134:137], v225 offset:34816
	ds_read_b128 v[138:141], v225 offset:36864
	ds_read_b128 v[142:145], v225 offset:38912
	ds_read_b128 v[226:229], v155 offset:2048
	ds_read_b128 v[238:241], v155 offset:4096
	s_and_b32 s38, s32, 1
	s_xor_b32 s38, s38, 1
	s_lshl_b32 s38, s38, 16
	s_waitcnt lgkmcnt(5)
	v_mfma_f32_16x16x32_bf16 v[98:101], v[130:133], v[150:153], v[98:101]
	ds_read_b128 v[248:251], v155 offset:6144
	s_waitcnt lgkmcnt(5)
	v_mfma_f32_16x16x32_bf16 v[58:61], v[134:137], v[150:153], v[58:61]
	s_waitcnt lgkmcnt(4)
	v_mfma_f32_16x16x32_bf16 v[26:29], v[138:141], v[150:153], v[26:29]
	s_add_u32 m0, s38, s19
	s_nop 0
	global_load_lds_dwordx4 v255, s[24:25]
	s_waitcnt lgkmcnt(3)
	v_mfma_f32_16x16x32_bf16 v[70:73], v[142:145], v[150:153], v[70:73]
	s_waitcnt lgkmcnt(2)
	v_mfma_f32_16x16x32_bf16 v[94:97], v[130:133], v[226:229], v[94:97]
	ds_read_b128 v[150:153], v157
	v_mfma_f32_16x16x32_bf16 v[50:53], v[134:137], v[226:229], v[50:53]
	v_mfma_f32_16x16x32_bf16 v[14:17], v[138:141], v[226:229], v[14:17]
	s_add_u32 m0, m0, 0x2000
	s_add_u32 s38, s24, 0x20000
	s_addc_u32 s39, s25, 0
	global_load_lds_dwordx4 v255, s[38:39]
	v_mfma_f32_16x16x32_bf16 v[62:65], v[142:145], v[226:229], v[62:65]
	s_waitcnt lgkmcnt(2)
	v_mfma_f32_16x16x32_bf16 v[82:85], v[130:133], v[238:241], v[82:85]
	ds_read_b128 v[226:229], v157 offset:2048
	v_mfma_f32_16x16x32_bf16 v[42:45], v[134:137], v[238:241], v[42:45]
	ds_read_b128 v[146:149], v230 offset:32768
	v_mfma_f32_16x16x32_bf16 v[6:9], v[138:141], v[238:241], v[6:9]
	s_add_u32 m0, m0, 0x2000
	s_add_u32 s38, s24, 0x40000
	s_addc_u32 s39, s25, 0
	global_load_lds_dwordx4 v255, s[38:39]
	v_mfma_f32_16x16x32_bf16 v[34:37], v[142:145], v[238:241], v[34:37]
	s_waitcnt lgkmcnt(3)
	v_mfma_f32_16x16x32_bf16 v[74:77], v[130:133], v[248:251], v[74:77]
	ds_read_b128 v[238:241], v157 offset:4096
	v_mfma_f32_16x16x32_bf16 v[38:41], v[134:137], v[248:251], v[38:41]
	ds_read_b128 v[134:137], v230 offset:34816
	v_mfma_f32_16x16x32_bf16 v[22:25], v[138:141], v[248:251], v[22:25]
	ds_read_b128 v[138:141], v230 offset:36864
	s_add_u32 m0, m0, 0x2000
	s_add_u32 s38, s24, 0x60000
	s_addc_u32 s39, s25, 0
	global_load_lds_dwordx4 v255, s[38:39]
	v_mfma_f32_16x16x32_bf16 v[110:113], v[142:145], v[248:251], v[110:113]
	ds_read_b128 v[142:145], v230 offset:38912
	s_waitcnt lgkmcnt(4)
	v_mfma_f32_16x16x32_bf16 v[98:101], v[146:149], v[150:153], v[98:101]
	ds_read_b128 v[248:251], v157 offset:6144
	s_waitcnt lgkmcnt(3)
	v_mfma_f32_16x16x32_bf16 v[58:61], v[134:137], v[150:153], v[58:61]
	s_waitcnt lgkmcnt(2)
	v_mfma_f32_16x16x32_bf16 v[26:29], v[138:141], v[150:153], v[26:29]
	s_add_u32 m0, m0, 0x2000
	s_nop 0
	global_load_lds_dwordx4 v255, s[26:27]
	s_waitcnt lgkmcnt(1)
	v_mfma_f32_16x16x32_bf16 v[70:73], v[142:145], v[150:153], v[70:73]
	v_mfma_f32_16x16x32_bf16 v[94:97], v[146:149], v[226:229], v[94:97]
	v_mfma_f32_16x16x32_bf16 v[50:53], v[134:137], v[226:229], v[50:53]
	v_mfma_f32_16x16x32_bf16 v[14:17], v[138:141], v[226:229], v[14:17]
	s_add_u32 m0, m0, 0x2000
	s_add_u32 s38, s26, 0x20000
	s_addc_u32 s39, s27, 0
	global_load_lds_dwordx4 v255, s[38:39]
	v_mfma_f32_16x16x32_bf16 v[62:65], v[142:145], v[226:229], v[62:65]
	v_mfma_f32_16x16x32_bf16 v[82:85], v[146:149], v[238:241], v[82:85]
	v_mfma_f32_16x16x32_bf16 v[42:45], v[134:137], v[238:241], v[42:45]
	v_mfma_f32_16x16x32_bf16 v[6:9], v[138:141], v[238:241], v[6:9]
	v_mfma_f32_16x16x32_bf16 v[34:37], v[142:145], v[238:241], v[34:37]
	s_waitcnt lgkmcnt(0)
	v_mfma_f32_16x16x32_bf16 v[74:77], v[146:149], v[248:251], v[74:77]
	v_mfma_f32_16x16x32_bf16 v[38:41], v[134:137], v[248:251], v[38:41]
	v_mfma_f32_16x16x32_bf16 v[22:25], v[138:141], v[248:251], v[22:25]
	v_mfma_f32_16x16x32_bf16 v[110:113], v[142:145], v[248:251], v[110:113]
	v_xor_b32_e32 v155, 0x10000, v155
	v_xor_b32_e32 v157, 0x10000, v157
	v_xor_b32_e32 v225, 0x10000, v225
	v_xor_b32_e32 v230, 0x10000, v230
	s_add_u32 s24, s24, 0x80
	s_addc_u32 s25, s25, 0
	s_add_u32 s26, s26, 0x80
	s_addc_u32 s27, s27, 0
	s_add_u32 s32, s32, 1
	s_cmp_lg_u32 s32, 14
	s_cbranch_scc1 .Lk_mgate
	v_cvt_pk_bf16_f32 v242, v2, v3
	s_waitcnt vmcnt(0)
	s_barrier
; DI f32x4 mfma16(bf16x8 a, bf16x8 b, f32x4 c) { return __builtin_amdgcn_mfma_f32_16x16x32_bf16(a, b, c, 0, 0, 0); }
; template <int MI, int NI>
; DI void gemm_kloop(const u16* Au, int lda, const u16* Bu, int ldb, int K, f32x4 (&acc)[NI][MI], unsigned char* smem) {
;     ...
;   for (int kt = 0; kt < nk; ++kt) {
;     __syncthreads();
;     if (kt + 1 < nk) {
;       SWRITE((kt + 1) & 1);
;       if (kt + 2 < nk) GLOAD((kt + 2) << 6);
;     }
;     {
;       const unsigned char* sa = smem + (kt & 1) * 65536;
;       const unsigned char* sb = sa + 32768;
; #pragma unroll
;       for (int ks = 0; ks < 2; ++ks) {
;         const int fo = ks ? fro1 : fro0;
;         bf16x8 af[MI];
; #pragma unroll
;         for (int i = 0; i < MI; ++i) af[i] = *(const bf16x8*)(sa + (wm * 16 * MI + i * 16) * 128 + fo);
; #pragma unroll
;         for (int nh = 0; nh < NI; nh += 4) {
;           bf16x8 wf[4];
; #pragma unroll
;           for (int i = 0; i < 4; ++i) wf[i] = *(const bf16x8*)(sb + (wn * 16 * NI + (nh + i) * 16) * 128 + fo);
; #pragma unroll
;           for (int ni = 0; ni < 4; ++ni)
; #pragma unroll
;             for (int mi = 0; mi < MI; ++mi) acc[nh + ni][mi] = mfma16(wf[ni], af[mi], acc[nh + ni][mi]);
;         }
;       }
;     }
;   }
;   __syncthreads();
; template <int MI>
; DI void merge_tile(const Params& p, int layer, int rowbase, int nt, unsigned char* smem) {
;     ...
;     u32 brp[4][MI][2];
; #pragma unroll
;     for (int ni = 0; ni < 4; ++ni)
; #pragma unroll
;       for (int mi = 0; mi < MI; ++mi) {
;         brp[ni][mi][0] = pack2bf(acc[ni][mi][0], acc[ni][mi][1]);
;         brp[ni][mi][1] = pack2bf(acc[ni][mi][2], acc[ni][mi][3]);
;       }
	s_add_u32 m0, s19, 0x10000
	s_nop 0
	global_load_lds_dwordx4 v255, s[24:25]
	s_add_u32 m0, m0, 0x2000
	s_add_u32 s38, s24, 0x20000
	s_addc_u32 s39, s25, 0
	global_load_lds_dwordx4 v255, s[38:39]
	s_add_u32 m0, m0, 0x2000
	s_add_u32 s38, s24, 0x40000
	s_addc_u32 s39, s25, 0
	global_load_lds_dwordx4 v255, s[38:39]
	s_add_u32 m0, m0, 0x2000
	s_add_u32 s38, s24, 0x60000
	s_addc_u32 s39, s25, 0
	global_load_lds_dwordx4 v255, s[38:39]
	s_add_u32 m0, m0, 0x2000
	s_nop 0
	global_load_lds_dwordx4 v255, s[26:27]
	s_add_u32 m0, m0, 0x2000
	s_add_u32 s38, s26, 0x20000
	s_addc_u32 s39, s27, 0
	global_load_lds_dwordx4 v255, s[38:39]
	s_mov_b32 s24, 0x58000
	s_mov_b32 s25, 0xefa18f08
	s_mov_b32 s26, 0x3f317217
	s_mov_b32 s27, 0x7f800000
	s_mov_b32 s38, 0x3e38aa3b
	s_brev_b32 s39, 1
	v_cvt_pk_bf16_f32 v193, v30, v31
	v_add_u32_e32 v30, v234, v233
	v_cvt_pk_bf16_f32 v241, v4, v5
	v_cvt_pk_bf16_f32 v231, v10, v11
	v_cvt_pk_bf16_f32 v230, v12, v13
	v_cvt_pk_bf16_f32 v226, v18, v19
	v_cvt_pk_bf16_f32 v225, v20, v21
	v_cvt_pk_bf16_f32 v192, v32, v33
	v_cvt_pk_bf16_f32 v236, v88, v89
	v_cvt_pk_bf16_f32 v89, v102, v103
	ds_read_b128 v[2:5], v30
	ds_read_b128 v[10:13], v30 offset:2048
	ds_read_b128 v[18:21], v30 offset:4096
	ds_read_b128 v[30:33], v30 offset:6144
	v_add_u32_e32 v103, v235, v233
	v_cvt_pk_bf16_f32 v240, v46, v47
	v_cvt_pk_bf16_f32 v239, v48, v49
	v_cvt_pk_bf16_f32 v229, v54, v55
	v_cvt_pk_bf16_f32 v228, v56, v57
	v_cvt_pk_bf16_f32 v195, v66, v67
	v_cvt_pk_bf16_f32 v194, v68, v69
	v_cvt_pk_bf16_f32 v155, v80, v81
	v_cvt_pk_bf16_f32 v88, v104, v105
	v_cvt_pk_bf16_f32 v81, v106, v107
	ds_read_b128 v[46:49], v103 offset:32768
	ds_read_b128 v[54:57], v103 offset:34816
	ds_read_b128 v[66:69], v103 offset:36864
	ds_read_b128 v[104:107], v103 offset:38912
	s_waitcnt lgkmcnt(1)
	v_mfma_f32_16x16x32_bf16 v[26:29], v[66:69], v[2:5], v[26:29]
	v_add_u32_e32 v103, v235, v232
	v_cvt_pk_bf16_f32 v80, v108, v109
	v_cvt_pk_bf16_f32 v238, v86, v87
	v_mfma_f32_16x16x32_bf16 v[14:17], v[66:69], v[10:13], v[14:17]
	v_cvt_pk_bf16_f32 v86, v124, v125
	v_or_b32_e32 v124, 0x18000, v235
	v_cvt_pk_bf16_f32 v227, v90, v91
	v_mfma_f32_16x16x32_bf16 v[6:9], v[66:69], v[18:21], v[6:9]
	v_cvt_pk_bf16_f32 v92, v92, v93
	v_cvt_pk_bf16_f32 v102, v114, v115
	v_cvt_pk_bf16_f32 v93, v116, v117
	v_mfma_f32_16x16x32_bf16 v[22:25], v[66:69], v[30:33], v[22:25]
	v_add_u32_e32 v66, v234, v232
	v_cvt_pk_bf16_f32 v91, v118, v119
	v_cvt_pk_bf16_f32 v90, v120, v121
	v_mfma_f32_16x16x32_bf16 v[98:101], v[46:49], v[2:5], v[98:101]
	v_cvt_pk_bf16_f32 v87, v122, v123
	v_cvt_pk_bf16_f32 v157, v78, v79
	v_cvt_pk_bf16_f32 v79, v126, v127
	v_mfma_f32_16x16x32_bf16 v[94:97], v[46:49], v[10:13], v[94:97]
	v_cvt_pk_bf16_f32 v78, v128, v129
	s_lshl_b64 s[2:3], s[10:11], 2
	s_add_u32 s2, s9, s2
	v_mfma_f32_16x16x32_bf16 v[82:85], v[46:49], v[18:21], v[82:85]
	s_addc_u32 s3, s59, s3
	s_add_i32 s66, s66, 1
	s_addk_i32 s54, 0x400
	v_mfma_f32_16x16x32_bf16 v[46:49], v[46:49], v[30:33], v[74:77]
	s_cmp_eq_u32 s66, 3
	v_mfma_f32_16x16x32_bf16 v[58:61], v[54:57], v[2:5], v[58:61]
	v_mfma_f32_16x16x32_bf16 v[50:53], v[54:57], v[10:13], v[50:53]
	v_mfma_f32_16x16x32_bf16 v[42:45], v[54:57], v[18:21], v[42:45]
	v_mfma_f32_16x16x32_bf16 v[38:41], v[54:57], v[30:33], v[38:41]
	s_waitcnt lgkmcnt(0)
	v_mfma_f32_16x16x32_bf16 v[2:5], v[104:107], v[2:5], v[70:73]
	v_mfma_f32_16x16x32_bf16 v[10:13], v[104:107], v[10:13], v[62:65]
	v_mfma_f32_16x16x32_bf16 v[18:21], v[104:107], v[18:21], v[34:37]
	s_nop 2
	ds_read_b128 v[34:37], v66
	ds_read_b128 v[54:57], v66 offset:2048
	ds_read_b128 v[62:65], v66 offset:4096
	ds_read_b128 v[66:69], v66 offset:6144
	v_mfma_f32_16x16x32_bf16 v[30:33], v[104:107], v[30:33], v[110:113]
	ds_read_b128 v[70:73], v103 offset:32768
	ds_read_b128 v[74:77], v103 offset:34816
	ds_read_b128 v[104:107], v103 offset:36864
	ds_read_b128 v[108:111], v103 offset:38912
	v_add_u32_e32 v103, 0x10000, v234
	s_waitcnt lgkmcnt(0)
	v_mfma_f32_16x16x32_bf16 v[46:49], v[70:73], v[66:69], v[46:49]
	s_waitcnt vmcnt(0)
	s_barrier
	v_mfma_f32_16x16x32_bf16 v[38:41], v[74:77], v[66:69], v[38:41]
	v_mfma_f32_16x16x32_bf16 v[22:25], v[104:107], v[66:69], v[22:25]
	v_mfma_f32_16x16x32_bf16 v[2:5], v[108:111], v[34:37], v[2:5]
	v_mfma_f32_16x16x32_bf16 v[10:13], v[108:111], v[54:57], v[10:13]
	v_mfma_f32_16x16x32_bf16 v[18:21], v[108:111], v[62:65], v[18:21]
	v_mfma_f32_16x16x32_bf16 v[30:33], v[108:111], v[66:69], v[30:33]
	v_add_u32_e32 v66, v103, v233
	v_add_u32_e32 v108, v124, v233
	v_mfma_f32_16x16x32_bf16 v[98:101], v[70:73], v[34:37], v[98:101]
	v_mfma_f32_16x16x32_bf16 v[94:97], v[70:73], v[54:57], v[94:97]
	v_mfma_f32_16x16x32_bf16 v[82:85], v[70:73], v[62:65], v[82:85]
	v_mfma_f32_16x16x32_bf16 v[58:61], v[74:77], v[34:37], v[58:61]
	v_mfma_f32_16x16x32_bf16 v[50:53], v[74:77], v[54:57], v[50:53]
	v_mfma_f32_16x16x32_bf16 v[42:45], v[74:77], v[62:65], v[42:45]
	v_mfma_f32_16x16x32_bf16 v[26:29], v[104:107], v[34:37], v[26:29]
	v_mfma_f32_16x16x32_bf16 v[14:17], v[104:107], v[54:57], v[14:17]
	v_mfma_f32_16x16x32_bf16 v[6:9], v[104:107], v[62:65], v[6:9]
	ds_read_b128 v[34:37], v66
	ds_read_b128 v[54:57], v66 offset:2048
	ds_read_b128 v[62:65], v66 offset:4096
	ds_read_b128 v[66:69], v66 offset:6144
	ds_read_b128 v[70:73], v108
	ds_read_b128 v[74:77], v108 offset:2048
	ds_read_b128 v[104:107], v108 offset:4096
	ds_read_b128 v[108:111], v108 offset:6144
	s_waitcnt lgkmcnt(3)
	v_mfma_f32_16x16x32_bf16 v[98:101], v[70:73], v[34:37], v[98:101]
	s_waitcnt lgkmcnt(2)
	v_mfma_f32_16x16x32_bf16 v[58:61], v[74:77], v[34:37], v[58:61]
	s_waitcnt lgkmcnt(1)
	v_mfma_f32_16x16x32_bf16 v[26:29], v[104:107], v[34:37], v[26:29]
	s_waitcnt lgkmcnt(0)
	v_mfma_f32_16x16x32_bf16 v[2:5], v[108:111], v[34:37], v[2:5]
	v_mfma_f32_16x16x32_bf16 v[34:37], v[108:111], v[54:57], v[10:13]
	s_nop 2
	v_add_u32_e32 v10, v103, v232
	v_mfma_f32_16x16x32_bf16 v[94:97], v[70:73], v[54:57], v[94:97]
	v_mfma_f32_16x16x32_bf16 v[82:85], v[70:73], v[62:65], v[82:85]
	v_mfma_f32_16x16x32_bf16 v[70:73], v[70:73], v[66:69], v[46:49]
	v_mfma_f32_16x16x32_bf16 v[50:53], v[74:77], v[54:57], v[50:53]
	v_mfma_f32_16x16x32_bf16 v[42:45], v[74:77], v[62:65], v[42:45]
	v_mfma_f32_16x16x32_bf16 v[38:41], v[74:77], v[66:69], v[38:41]
	v_mfma_f32_16x16x32_bf16 v[74:77], v[104:107], v[54:57], v[14:17]
	v_mfma_f32_16x16x32_bf16 v[6:9], v[104:107], v[62:65], v[6:9]
	v_mfma_f32_16x16x32_bf16 v[104:107], v[104:107], v[66:69], v[22:25]
	v_mfma_f32_16x16x32_bf16 v[112:115], v[108:111], v[62:65], v[18:21]
	v_mfma_f32_16x16x32_bf16 v[30:33], v[108:111], v[66:69], v[30:33]
	ds_read_b128 v[66:69], v10
	ds_read_b128 v[108:111], v10 offset:2048
	ds_read_b128 v[116:119], v10 offset:4096
	ds_read_b128 v[120:123], v10 offset:6144
	v_add_u32_e32 v18, v124, v232
	ds_read_b128 v[10:13], v18
	ds_read_b128 v[14:17], v18 offset:2048
	ds_read_b128 v[124:127], v18 offset:4096
	ds_read_b128 v[128:131], v18 offset:6144
	s_waitcnt lgkmcnt(3)
	v_mfma_f32_16x16x32_bf16 v[98:101], v[10:13], v[66:69], v[98:101]
	s_waitcnt lgkmcnt(0)
	s_barrier
; template <int MI>
; DI void merge_tile(const Params& p, int layer, int rowbase, int nt, unsigned char* smem) {
;     ...
; #pragma unroll
;     for (int mi = 0; mi < MI; ++mi) {
;       const float rs = rsqrtf(rowss[m0 + mi * 16] * (1.f / DM) + EPS);
; #pragma unroll
;       for (int ni = 0; ni < 4; ++ni) {
;         const float4 b4 = *(const float4*)(bg + br * DM + n0 + ni * 16);
;         const float bb[4] = {b4.x, b4.y, b4.z, b4.w};
;         float mv[4];
; #pragma unroll
;         for (int r = 0; r < 4; ++r) {
;           const float gv = acc[ni][mi][r] * rs + bb[r];
;           const float sg = 1.f / (1.f + __expf(-gv));
;           const u32 w = brp[ni][mi][r >> 1], mw = mp[ni][mi][r >> 1];
;           const float bv = __uint_as_float((r & 1) ? (w & 0xffff0000u) : (w << 16));
;           const float mo = __uint_as_float((r & 1) ? (mw & 0xffff0000u) : (mw << 16));
;           mv[r] = mo + sg * bv;
;         }
;         mp[ni][mi][0] = pack2bf(mv[0], mv[1]);
;         mp[ni][mi][1] = pack2bf(mv[2], mv[3]);
;       }
	v_mfma_f32_16x16x32_bf16 v[62:65], v[10:13], v[108:111], v[94:97]
	v_mfma_f32_16x16x32_bf16 v[46:49], v[10:13], v[116:119], v[82:85]
	v_mfma_f32_16x16x32_bf16 v[22:25], v[10:13], v[120:123], v[70:73]
	v_mfma_f32_16x16x32_bf16 v[10:13], v[124:127], v[66:69], v[26:29]
	s_nop 2
	v_mov_b32_e32 v26, v156
	v_mov_b32_e32 v28, v154
	v_mfma_f32_16x16x32_bf16 v[18:21], v[14:17], v[66:69], v[58:61]
	v_ashrrev_i32_e32 v27, 31, v26
	v_lshl_add_u64 v[70:71], v[26:27], 2, s[40:41]
	global_load_dword v26, v[70:71], off
	v_ashrrev_i32_e32 v29, 31, v28
	v_lshl_add_u64 v[72:73], v[28:29], 2, s[2:3]
	v_mfma_f32_16x16x32_bf16 v[66:69], v[128:131], v[66:69], v[2:5]
	v_lshlrev_b32_e32 v28, 16, v242
	v_and_b32_e32 v29, 0xffff0000, v242
	s_waitcnt vmcnt(0)
	v_fmamk_f32 v26, v26, 0x3a800000, v199
	v_mfma_f32_16x16x32_bf16 v[2:5], v[128:131], v[120:123], v[30:33]
	v_cmp_gt_f32_e32 vcc, s14, v26
	v_mul_f32_e32 v27, 0x4b800000, v26
	s_nop 0
	global_load_dwordx4 v[30:33], v[72:73], off
	v_cndmask_b32_e32 v26, v26, v27, vcc
	v_rsq_f32_e32 v26, v26
	v_mfma_f32_16x16x32_bf16 v[54:57], v[124:127], v[108:111], v[74:77]
	v_mul_f32_e32 v27, 0x45800000, v26
	v_cndmask_b32_e32 v82, v26, v27, vcc
	s_nop 0
	v_lshlrev_b32_e32 v74, 16, v176
	v_and_b32_e32 v75, 0xffff0000, v176
	v_mfma_f32_16x16x32_bf16 v[58:61], v[14:17], v[108:111], v[50:53]
	s_waitcnt vmcnt(0)
	v_fma_f32 v26, v98, v82, v30
	v_fma_f32 v27, v99, v82, v31
	v_mul_f32_e32 v26, 0xbfb8aa3b, v26
	v_mul_f32_e32 v27, 0xbfb8aa3b, v27
	v_exp_f32_e32 v26, v26
	v_exp_f32_e32 v27, v27
	v_mfma_f32_16x16x32_bf16 v[50:53], v[128:131], v[108:111], v[34:37]
	v_add_f32_e64 v26, v26, 1.0
	v_add_f32_e64 v27, v27, 1.0
	v_mfma_f32_16x16x32_bf16 v[42:45], v[14:17], v[116:119], v[42:45]
	v_rcp_f32_e32 v27, v27
	s_nop 0
	v_mfma_f32_16x16x32_bf16 v[14:17], v[14:17], v[120:123], v[38:41]
	v_rcp_f32_e32 v26, v26
	s_nop 0
	v_pk_fma_f32 v[26:27], v[26:27], v[28:29], v[74:75]
	v_fma_f32 v28, v100, v82, v32
	v_fma_f32 v29, v101, v82, v33
	v_mul_f32_e32 v28, 0xbfb8aa3b, v28
	v_mul_f32_e32 v29, 0xbfb8aa3b, v29
	v_exp_f32_e32 v28, v28
	v_exp_f32_e32 v29, v29
	v_lshlrev_b32_e32 v74, 16, v241
	v_lshlrev_b32_e32 v76, 16, v177
	v_and_b32_e32 v75, 0xffff0000, v241
	v_pk_add_f32 v[28:29], v[28:29], 1.0 op_sel_hi:[1,0]
	v_and_b32_e32 v77, 0xffff0000, v177
	v_cvt_pk_bf16_f32 v176, v26, v27
	v_mfma_f32_16x16x32_bf16 v[38:41], v[124:127], v[116:119], v[6:9]
	v_rcp_f32_e32 v29, v29
	s_nop 0
	v_mfma_f32_16x16x32_bf16 v[34:37], v[128:131], v[116:119], v[112:115]
	v_rcp_f32_e32 v28, v28
	s_nop 0
	v_pk_fma_f32 v[28:29], v[28:29], v[74:75], v[76:77]
	v_lshlrev_b32_e32 v74, 16, v240
	v_cvt_pk_bf16_f32 v177, v28, v29
	global_load_dwordx4 v[26:29], v[72:73], off offset:64
	v_lshlrev_b32_e32 v76, 16, v180
	v_and_b32_e32 v75, 0xffff0000, v240
	v_and_b32_e32 v77, 0xffff0000, v180
	v_mfma_f32_16x16x32_bf16 v[6:9], v[124:127], v[120:123], v[104:107]
	s_waitcnt vmcnt(0)
	v_fma_f32 v18, v18, v82, v26
	v_fma_f32 v19, v19, v82, v27
	v_mul_f32_e32 v18, 0xbfb8aa3b, v18
	v_mul_f32_e32 v19, 0xbfb8aa3b, v19
	v_exp_f32_e32 v18, v18
	v_exp_f32_e32 v19, v19
	v_fma_f32 v20, v20, v82, v28
	v_fma_f32 v21, v21, v82, v29
	v_mul_f32_e32 v20, 0xbfb8aa3b, v20
	v_pk_add_f32 v[18:19], v[18:19], 1.0 op_sel_hi:[1,0]
	v_mul_f32_e32 v21, 0xbfb8aa3b, v21
	v_exp_f32_e32 v20, v20
	v_exp_f32_e32 v21, v21
	v_rcp_f32_e32 v19, v19
	s_nop 0
	v_pk_add_f32 v[20:21], v[20:21], 1.0 op_sel_hi:[1,0]
	v_rcp_f32_e32 v18, v18
	s_nop 0
	v_pk_fma_f32 v[18:19], v[18:19], v[74:75], v[76:77]
	v_lshlrev_b32_e32 v74, 16, v239
	v_lshlrev_b32_e32 v76, 16, v181
	v_rcp_f32_e32 v21, v21
	s_nop 0
	v_and_b32_e32 v75, 0xffff0000, v239
	v_and_b32_e32 v77, 0xffff0000, v181
	v_cvt_pk_bf16_f32 v180, v18, v19
	v_rcp_f32_e32 v20, v20
	s_nop 0
	v_pk_fma_f32 v[20:21], v[20:21], v[74:75], v[76:77]
	v_lshlrev_b32_e32 v74, 16, v238
	v_cvt_pk_bf16_f32 v181, v20, v21
	global_load_dwordx4 v[18:21], v[72:73], off offset:128
	v_lshlrev_b32_e32 v76, 16, v184
	v_and_b32_e32 v75, 0xffff0000, v238
	v_and_b32_e32 v77, 0xffff0000, v184
	s_waitcnt vmcnt(0)
	v_fma_f32 v10, v10, v82, v18
	v_fma_f32 v11, v11, v82, v19
	v_mul_f32_e32 v10, 0xbfb8aa3b, v10
	v_mul_f32_e32 v11, 0xbfb8aa3b, v11
	v_exp_f32_e32 v10, v10
	v_exp_f32_e32 v11, v11
	v_fma_f32 v12, v12, v82, v20
	v_fma_f32 v13, v13, v82, v21
	v_mul_f32_e32 v12, 0xbfb8aa3b, v12
	v_pk_add_f32 v[10:11], v[10:11], 1.0 op_sel_hi:[1,0]
	v_mul_f32_e32 v13, 0xbfb8aa3b, v13
	v_exp_f32_e32 v12, v12
	v_exp_f32_e32 v13, v13
	v_rcp_f32_e32 v11, v11
	s_nop 0
	v_pk_add_f32 v[12:13], v[12:13], 1.0 op_sel_hi:[1,0]
	v_rcp_f32_e32 v10, v10
	s_nop 0
	v_pk_fma_f32 v[10:11], v[10:11], v[74:75], v[76:77]
	v_lshlrev_b32_e32 v74, 16, v236
	v_lshlrev_b32_e32 v76, 16, v185
	v_rcp_f32_e32 v13, v13
	s_nop 0
	v_and_b32_e32 v75, 0xffff0000, v236
	v_and_b32_e32 v77, 0xffff0000, v185
	v_cvt_pk_bf16_f32 v184, v10, v11
	v_rcp_f32_e32 v12, v12
	s_nop 0
	v_pk_fma_f32 v[12:13], v[12:13], v[74:75], v[76:77]
	v_lshlrev_b32_e32 v74, 16, v190
	v_cvt_pk_bf16_f32 v185, v12, v13
	global_load_dwordx4 v[10:13], v[72:73], off offset:192
	v_lshlrev_b32_e32 v72, 16, v102
	v_and_b32_e32 v73, 0xffff0000, v102
	v_and_b32_e32 v75, 0xffff0000, v190
	s_waitcnt vmcnt(0)
	v_fma_f32 v66, v66, v82, v10
	v_fma_f32 v67, v67, v82, v11
	v_mul_f32_e32 v66, 0xbfb8aa3b, v66
	v_mul_f32_e32 v67, 0xbfb8aa3b, v67
	v_exp_f32_e32 v66, v66
	v_exp_f32_e32 v67, v67
	v_fma_f32 v68, v68, v82, v12
	v_fma_f32 v69, v69, v82, v13
	v_mul_f32_e32 v68, 0xbfb8aa3b, v68
	v_pk_add_f32 v[66:67], v[66:67], 1.0 op_sel_hi:[1,0]
	v_mul_f32_e32 v69, 0xbfb8aa3b, v69
	v_exp_f32_e32 v68, v68
	v_exp_f32_e32 v69, v69
	v_rcp_f32_e32 v67, v67
	s_nop 0
	v_pk_add_f32 v[68:69], v[68:69], 1.0 op_sel_hi:[1,0]
	v_rcp_f32_e32 v66, v66
	s_nop 0
	v_pk_fma_f32 v[66:67], v[66:67], v[72:73], v[74:75]
	v_cvt_pk_bf16_f32 v190, v66, v67
	global_load_dword v66, v[70:71], off offset:64
	v_lshlrev_b32_e32 v72, 16, v93
	v_lshlrev_b32_e32 v74, 16, v191
	v_and_b32_e32 v73, 0xffff0000, v93
	v_rcp_f32_e32 v69, v69
	s_nop 0
	v_and_b32_e32 v75, 0xffff0000, v191
	v_rcp_f32_e32 v68, v68
	s_nop 0
	v_pk_fma_f32 v[68:69], v[68:69], v[72:73], v[74:75]
	s_waitcnt vmcnt(0)
; template <int MI>
; DI void merge_tile(const Params& p, int layer, int rowbase, int nt, unsigned char* smem) {
;     ...
; #pragma unroll
;     for (int mi = 0; mi < MI; ++mi) {
;       const float rs = rsqrtf(rowss[m0 + mi * 16] * (1.f / DM) + EPS);
; #pragma unroll
;       for (int ni = 0; ni < 4; ++ni) {
;         const float4 b4 = *(const float4*)(bg + br * DM + n0 + ni * 16);
;         const float bb[4] = {b4.x, b4.y, b4.z, b4.w};
;         float mv[4];
; #pragma unroll
;         for (int r = 0; r < 4; ++r) {
;           const float gv = acc[ni][mi][r] * rs + bb[r];
;           const float sg = 1.f / (1.f + __expf(-gv));
;           const u32 w = brp[ni][mi][r >> 1], mw = mp[ni][mi][r >> 1];
;           const float bv = __uint_as_float((r & 1) ? (w & 0xffff0000u) : (w << 16));
;           const float mo = __uint_as_float((r & 1) ? (mw & 0xffff0000u) : (mw << 16));
;           mv[r] = mo + sg * bv;
;         }
;         mp[ni][mi][0] = pack2bf(mv[0], mv[1]);
;         mp[ni][mi][1] = pack2bf(mv[2], mv[3]);
;       }
	v_fmamk_f32 v66, v66, 0x3a800000, v199
	v_cmp_gt_f32_e32 vcc, s14, v66
	v_mul_f32_e32 v67, 0x4b800000, v66
	v_cvt_pk_bf16_f32 v191, v68, v69
	v_cndmask_b32_e32 v66, v66, v67, vcc
	v_rsq_f32_e32 v66, v66
	v_lshlrev_b32_e32 v68, 16, v168
	v_and_b32_e32 v69, 0xffff0000, v168
	v_mul_f32_e32 v67, 0x45800000, v66
	v_cndmask_b32_e32 v72, v66, v67, vcc
	v_fma_f32 v62, v62, v72, v30
	v_fma_f32 v63, v63, v72, v31
	v_mul_f32_e32 v62, 0xbfb8aa3b, v62
	v_mul_f32_e32 v63, 0xbfb8aa3b, v63
	v_exp_f32_e32 v62, v62
	v_exp_f32_e32 v63, v63
	v_fma_f32 v64, v64, v72, v32
	v_fma_f32 v65, v65, v72, v33
	v_mul_f32_e32 v64, 0xbfb8aa3b, v64
	v_pk_add_f32 v[62:63], v[62:63], 1.0 op_sel_hi:[1,0]
	v_mul_f32_e32 v65, 0xbfb8aa3b, v65
	v_exp_f32_e32 v64, v64
	v_exp_f32_e32 v65, v65
	v_fma_f32 v58, v58, v72, v26
	v_rcp_f32_e32 v63, v63
	s_nop 0
	v_pk_add_f32 v[64:65], v[64:65], 1.0 op_sel_hi:[1,0]
	v_fma_f32 v59, v59, v72, v27
	v_mul_f32_e32 v58, 0xbfb8aa3b, v58
	v_rcp_f32_e32 v62, v62
	s_nop 0
	v_mul_f32_e32 v59, 0xbfb8aa3b, v59
	v_exp_f32_e32 v58, v58
	v_exp_f32_e32 v59, v59
	v_rcp_f32_e32 v65, v65
	s_nop 0
	v_lshlrev_b32_e32 v66, 16, v231
	v_and_b32_e32 v67, 0xffff0000, v231
	v_pk_fma_f32 v[62:63], v[62:63], v[66:67], v[68:69]
	v_lshlrev_b32_e32 v66, 16, v230
	v_lshlrev_b32_e32 v68, 16, v169
	v_and_b32_e32 v67, 0xffff0000, v230
	v_and_b32_e32 v69, 0xffff0000, v169
	v_rcp_f32_e32 v64, v64
	s_nop 0
	v_pk_add_f32 v[58:59], v[58:59], 1.0 op_sel_hi:[1,0]
	v_pk_fma_f32 v[64:65], v[64:65], v[66:67], v[68:69]
	v_fma_f32 v60, v60, v72, v28
	v_fma_f32 v61, v61, v72, v29
	v_mul_f32_e32 v60, 0xbfb8aa3b, v60
	v_rcp_f32_e32 v59, v59
	s_nop 0
	v_mul_f32_e32 v61, 0xbfb8aa3b, v61
	v_exp_f32_e32 v60, v60
	v_exp_f32_e32 v61, v61
	s_nop 0
	v_pk_add_f32 v[60:61], v[60:61], 1.0 op_sel_hi:[1,0]
	v_rcp_f32_e32 v58, v58
	s_nop 0
	v_fma_f32 v54, v54, v72, v18
	v_fma_f32 v55, v55, v72, v19
	v_mul_f32_e32 v54, 0xbfb8aa3b, v54
	v_rcp_f32_e32 v61, v61
	s_nop 0
	v_mul_f32_e32 v55, 0xbfb8aa3b, v55
	v_exp_f32_e32 v54, v54
	v_exp_f32_e32 v55, v55
	v_cvt_pk_bf16_f32 v168, v62, v63
	v_cvt_pk_bf16_f32 v169, v64, v65
	v_lshlrev_b32_e32 v62, 16, v229
	v_lshlrev_b32_e32 v64, 16, v170
	v_and_b32_e32 v63, 0xffff0000, v229
	v_and_b32_e32 v65, 0xffff0000, v170
	v_pk_fma_f32 v[58:59], v[58:59], v[62:63], v[64:65]
	v_lshlrev_b32_e32 v62, 16, v228
	v_lshlrev_b32_e32 v64, 16, v171
	v_and_b32_e32 v63, 0xffff0000, v228
	v_and_b32_e32 v65, 0xffff0000, v171
	v_rcp_f32_e32 v60, v60
	s_nop 0
	v_pk_add_f32 v[54:55], v[54:55], 1.0 op_sel_hi:[1,0]
	v_pk_fma_f32 v[60:61], v[60:61], v[62:63], v[64:65]
	v_fma_f32 v56, v56, v72, v20
	v_fma_f32 v57, v57, v72, v21
	v_mul_f32_e32 v56, 0xbfb8aa3b, v56
	v_rcp_f32_e32 v55, v55
	s_nop 0
	v_mul_f32_e32 v57, 0xbfb8aa3b, v57
	v_exp_f32_e32 v56, v56
	v_exp_f32_e32 v57, v57
	s_nop 0
	v_pk_add_f32 v[56:57], v[56:57], 1.0 op_sel_hi:[1,0]
	v_rcp_f32_e32 v54, v54
	s_nop 0
	v_fma_f32 v50, v50, v72, v10
	v_fma_f32 v51, v51, v72, v11
	v_mul_f32_e32 v50, 0xbfb8aa3b, v50
	v_rcp_f32_e32 v57, v57
	s_nop 0
	v_mul_f32_e32 v51, 0xbfb8aa3b, v51
	v_exp_f32_e32 v50, v50
	v_exp_f32_e32 v51, v51
	v_cvt_pk_bf16_f32 v170, v58, v59
	v_cvt_pk_bf16_f32 v171, v60, v61
	v_lshlrev_b32_e32 v58, 16, v227
	v_lshlrev_b32_e32 v60, 16, v172
	v_and_b32_e32 v59, 0xffff0000, v227
	v_and_b32_e32 v61, 0xffff0000, v172
	v_pk_fma_f32 v[54:55], v[54:55], v[58:59], v[60:61]
	v_lshlrev_b32_e32 v58, 16, v92
	v_lshlrev_b32_e32 v60, 16, v173
	v_and_b32_e32 v59, 0xffff0000, v92
	v_and_b32_e32 v61, 0xffff0000, v173
	v_rcp_f32_e32 v56, v56
	s_nop 0
	v_pk_add_f32 v[50:51], v[50:51], 1.0 op_sel_hi:[1,0]
	v_pk_fma_f32 v[56:57], v[56:57], v[58:59], v[60:61]
	v_cvt_pk_bf16_f32 v172, v54, v55
	v_cvt_pk_bf16_f32 v173, v56, v57
	v_lshlrev_b32_e32 v54, 16, v91
	v_rcp_f32_e32 v51, v51
	s_nop 0
	v_lshlrev_b32_e32 v56, 16, v174
	v_and_b32_e32 v55, 0xffff0000, v91
	v_and_b32_e32 v57, 0xffff0000, v174
	v_rcp_f32_e32 v50, v50
	s_nop 0
	v_pk_fma_f32 v[50:51], v[50:51], v[54:55], v[56:57]
	v_fma_f32 v52, v52, v72, v12
	v_cvt_pk_bf16_f32 v174, v50, v51
	global_load_dword v50, v[70:71], off offset:128
	v_fma_f32 v53, v53, v72, v13
	v_mul_f32_e32 v52, 0xbfb8aa3b, v52
	v_mul_f32_e32 v53, 0xbfb8aa3b, v53
	v_exp_f32_e32 v52, v52
	v_exp_f32_e32 v53, v53
	v_lshlrev_b32_e32 v54, 16, v90
	v_lshlrev_b32_e32 v56, 16, v175
	v_and_b32_e32 v55, 0xffff0000, v90
	v_pk_add_f32 v[52:53], v[52:53], 1.0 op_sel_hi:[1,0]
	v_and_b32_e32 v57, 0xffff0000, v175
	s_waitcnt vmcnt(0)
; template <int MI>
; DI void merge_tile(const Params& p, int layer, int rowbase, int nt, unsigned char* smem) {
;     ...
; #pragma unroll
;     for (int mi = 0; mi < MI; ++mi) {
;       const float rs = rsqrtf(rowss[m0 + mi * 16] * (1.f / DM) + EPS);
; #pragma unroll
;       for (int ni = 0; ni < 4; ++ni) {
;         const float4 b4 = *(const float4*)(bg + br * DM + n0 + ni * 16);
;         const float bb[4] = {b4.x, b4.y, b4.z, b4.w};
;         float mv[4];
; #pragma unroll
;         for (int r = 0; r < 4; ++r) {
;           const float gv = acc[ni][mi][r] * rs + bb[r];
;           const float sg = 1.f / (1.f + __expf(-gv));
;           const u32 w = brp[ni][mi][r >> 1], mw = mp[ni][mi][r >> 1];
;           const float bv = __uint_as_float((r & 1) ? (w & 0xffff0000u) : (w << 16));
;           const float mo = __uint_as_float((r & 1) ? (mw & 0xffff0000u) : (mw << 16));
;           mv[r] = mo + sg * bv;
;         }
;         mp[ni][mi][0] = pack2bf(mv[0], mv[1]);
;         mp[ni][mi][1] = pack2bf(mv[2], mv[3]);
;       }
	v_fmamk_f32 v50, v50, 0x3a800000, v199
	v_rcp_f32_e32 v53, v53
	s_nop 0
	v_mul_f32_e32 v51, 0x4b800000, v50
	v_cmp_gt_f32_e32 vcc, s14, v50
	v_rcp_f32_e32 v52, v52
	s_nop 0
	v_pk_fma_f32 v[52:53], v[52:53], v[54:55], v[56:57]
	v_cndmask_b32_e32 v50, v50, v51, vcc
	v_rsq_f32_e32 v50, v50
	v_cvt_pk_bf16_f32 v175, v52, v53
	v_lshlrev_b32_e32 v52, 16, v158
	v_and_b32_e32 v53, 0xffff0000, v158
	v_mul_f32_e32 v51, 0x45800000, v50
	v_cndmask_b32_e32 v54, v50, v51, vcc
	v_fma_f32 v46, v46, v54, v30
	v_fma_f32 v47, v47, v54, v31
	v_mul_f32_e32 v46, 0xbfb8aa3b, v46
	v_mul_f32_e32 v47, 0xbfb8aa3b, v47
	v_exp_f32_e32 v46, v46
	v_exp_f32_e32 v47, v47
	v_fma_f32 v48, v48, v54, v32
	v_fma_f32 v49, v49, v54, v33
	v_mul_f32_e32 v48, 0xbfb8aa3b, v48
	v_pk_add_f32 v[46:47], v[46:47], 1.0 op_sel_hi:[1,0]
	v_mul_f32_e32 v49, 0xbfb8aa3b, v49
	v_exp_f32_e32 v48, v48
	v_exp_f32_e32 v49, v49
	v_fma_f32 v42, v42, v54, v26
	v_rcp_f32_e32 v47, v47
	s_nop 0
	v_pk_add_f32 v[48:49], v[48:49], 1.0 op_sel_hi:[1,0]
	v_fma_f32 v43, v43, v54, v27
	v_mul_f32_e32 v42, 0xbfb8aa3b, v42
	v_rcp_f32_e32 v46, v46
	s_nop 0
	v_mul_f32_e32 v43, 0xbfb8aa3b, v43
	v_exp_f32_e32 v42, v42
	v_exp_f32_e32 v43, v43
	v_rcp_f32_e32 v49, v49
	s_nop 0
	v_lshlrev_b32_e32 v50, 16, v226
	v_and_b32_e32 v51, 0xffff0000, v226
	v_pk_fma_f32 v[46:47], v[46:47], v[50:51], v[52:53]
	v_lshlrev_b32_e32 v50, 16, v225
	v_lshlrev_b32_e32 v52, 16, v159
	v_and_b32_e32 v51, 0xffff0000, v225
	v_and_b32_e32 v53, 0xffff0000, v159
	v_rcp_f32_e32 v48, v48
	s_nop 0
	v_pk_add_f32 v[42:43], v[42:43], 1.0 op_sel_hi:[1,0]
	v_pk_fma_f32 v[48:49], v[48:49], v[50:51], v[52:53]
	v_fma_f32 v44, v44, v54, v28
	v_fma_f32 v45, v45, v54, v29
	v_mul_f32_e32 v44, 0xbfb8aa3b, v44
	v_rcp_f32_e32 v43, v43
	s_nop 0
	v_mul_f32_e32 v45, 0xbfb8aa3b, v45
	v_exp_f32_e32 v44, v44
	v_exp_f32_e32 v45, v45
	s_nop 0
	v_pk_add_f32 v[44:45], v[44:45], 1.0 op_sel_hi:[1,0]
	v_rcp_f32_e32 v42, v42
	s_nop 0
	v_fma_f32 v38, v38, v54, v18
	v_fma_f32 v39, v39, v54, v19
	v_mul_f32_e32 v38, 0xbfb8aa3b, v38
	v_rcp_f32_e32 v45, v45
	s_nop 0
	v_mul_f32_e32 v39, 0xbfb8aa3b, v39
	v_exp_f32_e32 v38, v38
	v_exp_f32_e32 v39, v39
	v_cvt_pk_bf16_f32 v158, v46, v47
	v_cvt_pk_bf16_f32 v159, v48, v49
	v_lshlrev_b32_e32 v46, 16, v195
	v_lshlrev_b32_e32 v48, 16, v160
	v_and_b32_e32 v47, 0xffff0000, v195
	v_and_b32_e32 v49, 0xffff0000, v160
	v_pk_fma_f32 v[42:43], v[42:43], v[46:47], v[48:49]
	v_lshlrev_b32_e32 v46, 16, v194
	v_lshlrev_b32_e32 v48, 16, v161
	v_and_b32_e32 v47, 0xffff0000, v194
	v_and_b32_e32 v49, 0xffff0000, v161
	v_rcp_f32_e32 v44, v44
	s_nop 0
	v_pk_add_f32 v[38:39], v[38:39], 1.0 op_sel_hi:[1,0]
	v_pk_fma_f32 v[44:45], v[44:45], v[46:47], v[48:49]
	v_fma_f32 v40, v40, v54, v20
	v_fma_f32 v41, v41, v54, v21
	v_mul_f32_e32 v40, 0xbfb8aa3b, v40
	v_rcp_f32_e32 v39, v39
	s_nop 0
	v_mul_f32_e32 v41, 0xbfb8aa3b, v41
	v_exp_f32_e32 v40, v40
	v_exp_f32_e32 v41, v41
	s_nop 0
	v_pk_add_f32 v[40:41], v[40:41], 1.0 op_sel_hi:[1,0]
	v_rcp_f32_e32 v38, v38
	s_nop 0
	v_fma_f32 v34, v34, v54, v10
	v_fma_f32 v35, v35, v54, v11
	v_mul_f32_e32 v34, 0xbfb8aa3b, v34
	v_rcp_f32_e32 v41, v41
	s_nop 0
	v_mul_f32_e32 v35, 0xbfb8aa3b, v35
	v_exp_f32_e32 v34, v34
	v_exp_f32_e32 v35, v35
	v_cvt_pk_bf16_f32 v160, v42, v43
	v_cvt_pk_bf16_f32 v161, v44, v45
	v_lshlrev_b32_e32 v42, 16, v89
	v_lshlrev_b32_e32 v44, 16, v162
	v_and_b32_e32 v43, 0xffff0000, v89
	v_and_b32_e32 v45, 0xffff0000, v162
	v_pk_fma_f32 v[38:39], v[38:39], v[42:43], v[44:45]
	v_lshlrev_b32_e32 v42, 16, v88
	v_lshlrev_b32_e32 v44, 16, v163
	v_and_b32_e32 v43, 0xffff0000, v88
	v_and_b32_e32 v45, 0xffff0000, v163
	v_rcp_f32_e32 v40, v40
	s_nop 0
	v_pk_add_f32 v[34:35], v[34:35], 1.0 op_sel_hi:[1,0]
	v_pk_fma_f32 v[40:41], v[40:41], v[42:43], v[44:45]
	v_cvt_pk_bf16_f32 v162, v38, v39
	v_cvt_pk_bf16_f32 v163, v40, v41
	v_lshlrev_b32_e32 v38, 16, v87
	v_rcp_f32_e32 v35, v35
	s_nop 0
	v_lshlrev_b32_e32 v40, 16, v164
	v_and_b32_e32 v39, 0xffff0000, v87
	v_and_b32_e32 v41, 0xffff0000, v164
	v_rcp_f32_e32 v34, v34
	s_nop 0
	v_pk_fma_f32 v[34:35], v[34:35], v[38:39], v[40:41]
	v_fma_f32 v36, v36, v54, v12
	v_cvt_pk_bf16_f32 v164, v34, v35
	global_load_dword v34, v[70:71], off offset:192
	v_fma_f32 v37, v37, v54, v13
	v_mul_f32_e32 v36, 0xbfb8aa3b, v36
	v_mul_f32_e32 v37, 0xbfb8aa3b, v37
	v_exp_f32_e32 v36, v36
	v_exp_f32_e32 v37, v37
	v_lshlrev_b32_e32 v38, 16, v86
	v_lshlrev_b32_e32 v40, 16, v165
	v_and_b32_e32 v39, 0xffff0000, v86
	v_pk_add_f32 v[36:37], v[36:37], 1.0 op_sel_hi:[1,0]
	v_and_b32_e32 v41, 0xffff0000, v165
	s_waitcnt vmcnt(0)
; template <int MI>
; DI void merge_tile(const Params& p, int layer, int rowbase, int nt, unsigned char* smem) {
;     ...
; #pragma unroll
;     for (int mi = 0; mi < MI; ++mi) {
;       const float rs = rsqrtf(rowss[m0 + mi * 16] * (1.f / DM) + EPS);
; #pragma unroll
;       for (int ni = 0; ni < 4; ++ni) {
;         const float4 b4 = *(const float4*)(bg + br * DM + n0 + ni * 16);
;         const float bb[4] = {b4.x, b4.y, b4.z, b4.w};
;         float mv[4];
; #pragma unroll
;         for (int r = 0; r < 4; ++r) {
;           const float gv = acc[ni][mi][r] * rs + bb[r];
;           const float sg = 1.f / (1.f + __expf(-gv));
;           const u32 w = brp[ni][mi][r >> 1], mw = mp[ni][mi][r >> 1];
;           const float bv = __uint_as_float((r & 1) ? (w & 0xffff0000u) : (w << 16));
;           const float mo = __uint_as_float((r & 1) ? (mw & 0xffff0000u) : (mw << 16));
;           mv[r] = mo + sg * bv;
;         }
;         mp[ni][mi][0] = pack2bf(mv[0], mv[1]);
;         mp[ni][mi][1] = pack2bf(mv[2], mv[3]);
;       }
;     }
;   }
;   int m0 = rowbase + wm * 16 * MI + lm, n0 = nt * 128 + wn * 64 + lg * 4;
;   asm volatile("" : "+v"(m0), "+v"(n0));
; #pragma unroll
;   for (int mi = 0; mi < MI; ++mi)
; #pragma unroll
;     for (int ni = 0; ni < 4; ++ni) {
;       u32x2 pk = {mp[ni][mi][0], mp[ni][mi][1]};
;       *(u32x2*)(p.merged + (size_t)(m0 + mi * 16) * DM + n0 + ni * 16) = pk;
;     }
; DI void phase_merge(const Params& p, int layer, unsigned char* smem) {
;     ...
;   for (int it = vblock(); it < nfull; it += gridDim.x) {
;     const int g = it / (4 * NT), rem = it - g * (4 * NT), nt = rem >> 2, mt = g * 4 + (rem & 3);
;     merge_tile<4>(p, layer, mt * 256, nt, smem);
	v_fmamk_f32 v34, v34, 0x3a800000, v199
	v_rcp_f32_e32 v37, v37
	s_nop 0
	v_mul_f32_e32 v35, 0x4b800000, v34
	v_cmp_gt_f32_e32 vcc, s14, v34
	v_rcp_f32_e32 v36, v36
	s_nop 0
	v_pk_fma_f32 v[36:37], v[36:37], v[38:39], v[40:41]
	v_cndmask_b32_e32 v34, v34, v35, vcc
	v_rsq_f32_e32 v34, v34
	v_cvt_pk_bf16_f32 v165, v36, v37
	v_lshlrev_b32_e32 v36, 16, v178
	v_and_b32_e32 v37, 0xffff0000, v178
	v_mul_f32_e32 v35, 0x45800000, v34
	v_cndmask_b32_e32 v34, v34, v35, vcc
	v_fma_f32 v22, v22, v34, v30
	v_fma_f32 v23, v23, v34, v31
	v_mul_f32_e32 v22, 0xbfb8aa3b, v22
	v_mul_f32_e32 v23, 0xbfb8aa3b, v23
	v_exp_f32_e32 v22, v22
	v_exp_f32_e32 v23, v23
	v_fma_f32 v24, v24, v34, v32
	v_fmac_f32_e32 v33, v25, v34
	v_mul_f32_e32 v24, 0xbfb8aa3b, v24
	v_pk_add_f32 v[22:23], v[22:23], 1.0 op_sel_hi:[1,0]
	v_mul_f32_e32 v25, 0xbfb8aa3b, v33
	v_exp_f32_e32 v24, v24
	v_exp_f32_e32 v25, v25
	v_lshlrev_b32_e32 v30, 16, v193
	v_rcp_f32_e32 v23, v23
	s_nop 0
	v_pk_add_f32 v[24:25], v[24:25], 1.0 op_sel_hi:[1,0]
	v_and_b32_e32 v31, 0xffff0000, v193
	v_fma_f32 v14, v14, v34, v26
	v_rcp_f32_e32 v22, v22
	s_nop 0
	v_pk_fma_f32 v[22:23], v[22:23], v[30:31], v[36:37]
	v_fma_f32 v15, v15, v34, v27
	v_mul_f32_e32 v14, 0xbfb8aa3b, v14
	v_mul_f32_e32 v15, 0xbfb8aa3b, v15
	v_rcp_f32_e32 v25, v25
	s_nop 0
	v_exp_f32_e32 v14, v14
	v_exp_f32_e32 v15, v15
	v_lshlrev_b32_e32 v30, 16, v192
	v_pk_add_f32 v[14:15], v[14:15], 1.0 op_sel_hi:[1,0]
	v_lshlrev_b32_e32 v32, 16, v179
	v_and_b32_e32 v31, 0xffff0000, v192
	v_and_b32_e32 v33, 0xffff0000, v179
	v_rcp_f32_e32 v24, v24
	s_nop 0
	v_pk_fma_f32 v[24:25], v[24:25], v[30:31], v[32:33]
	v_rcp_f32_e32 v15, v15
	s_nop 0
	v_fma_f32 v16, v16, v34, v28
	v_fmac_f32_e32 v29, v17, v34
	v_mul_f32_e32 v16, 0xbfb8aa3b, v16
	v_mul_f32_e32 v17, 0xbfb8aa3b, v29
	v_exp_f32_e32 v16, v16
	v_exp_f32_e32 v17, v17
	s_nop 0
	v_pk_add_f32 v[16:17], v[16:17], 1.0 op_sel_hi:[1,0]
	v_rcp_f32_e32 v14, v14
	s_nop 0
	v_fma_f32 v6, v6, v34, v18
	v_fma_f32 v7, v7, v34, v19
	v_mul_f32_e32 v6, 0xbfb8aa3b, v6
	v_rcp_f32_e32 v17, v17
	s_nop 0
	v_mul_f32_e32 v7, 0xbfb8aa3b, v7
	v_exp_f32_e32 v6, v6
	v_exp_f32_e32 v7, v7
	s_nop 0
	v_pk_add_f32 v[6:7], v[6:7], 1.0 op_sel_hi:[1,0]
	v_cvt_pk_bf16_f32 v178, v22, v23
	v_cvt_pk_bf16_f32 v179, v24, v25
	v_lshlrev_b32_e32 v22, 16, v157
	v_lshlrev_b32_e32 v24, 16, v182
	v_and_b32_e32 v23, 0xffff0000, v157
	v_and_b32_e32 v25, 0xffff0000, v182
	v_pk_fma_f32 v[14:15], v[14:15], v[22:23], v[24:25]
	v_lshlrev_b32_e32 v22, 16, v155
	v_lshlrev_b32_e32 v24, 16, v183
	v_and_b32_e32 v23, 0xffff0000, v155
	v_and_b32_e32 v25, 0xffff0000, v183
	v_rcp_f32_e32 v16, v16
	s_nop 0
	v_pk_fma_f32 v[16:17], v[16:17], v[22:23], v[24:25]
	v_rcp_f32_e32 v7, v7
	s_nop 0
	v_fma_f32 v8, v8, v34, v20
	v_fmac_f32_e32 v21, v9, v34
	v_mul_f32_e32 v8, 0xbfb8aa3b, v8
	v_mul_f32_e32 v9, 0xbfb8aa3b, v21
	v_exp_f32_e32 v8, v8
	v_exp_f32_e32 v9, v9
	s_nop 0
	v_pk_add_f32 v[8:9], v[8:9], 1.0 op_sel_hi:[1,0]
	v_rcp_f32_e32 v6, v6
	s_nop 0
	v_fma_f32 v2, v2, v34, v10
	v_fma_f32 v3, v3, v34, v11
	v_mul_f32_e32 v2, 0xbfb8aa3b, v2
	v_rcp_f32_e32 v9, v9
	s_nop 0
	v_mul_f32_e32 v3, 0xbfb8aa3b, v3
	v_exp_f32_e32 v2, v2
	v_exp_f32_e32 v3, v3
	s_nop 0
	v_pk_add_f32 v[2:3], v[2:3], 1.0 op_sel_hi:[1,0]
	v_cvt_pk_bf16_f32 v182, v14, v15
	v_cvt_pk_bf16_f32 v183, v16, v17
	v_lshlrev_b32_e32 v14, 16, v81
	v_lshlrev_b32_e32 v16, 16, v188
	v_and_b32_e32 v15, 0xffff0000, v81
	v_and_b32_e32 v17, 0xffff0000, v188
	v_pk_fma_f32 v[6:7], v[6:7], v[14:15], v[16:17]
	v_lshlrev_b32_e32 v14, 16, v80
	v_lshlrev_b32_e32 v16, 16, v189
	v_and_b32_e32 v15, 0xffff0000, v80
	v_and_b32_e32 v17, 0xffff0000, v189
	v_rcp_f32_e32 v8, v8
	s_nop 0
	v_pk_fma_f32 v[8:9], v[8:9], v[14:15], v[16:17]
	v_rcp_f32_e32 v3, v3
	s_nop 0
	v_fma_f32 v4, v4, v34, v12
	v_fmac_f32_e32 v13, v5, v34
	v_mul_f32_e32 v4, 0xbfb8aa3b, v4
	v_mul_f32_e32 v5, 0xbfb8aa3b, v13
	v_exp_f32_e32 v4, v4
	v_exp_f32_e32 v5, v5
	s_nop 0
	v_pk_add_f32 v[4:5], v[4:5], 1.0 op_sel_hi:[1,0]
	v_rcp_f32_e32 v2, v2
	s_nop 0
	v_cvt_pk_bf16_f32 v188, v6, v7
	v_cvt_pk_bf16_f32 v189, v8, v9
	v_lshlrev_b32_e32 v6, 16, v79
	v_rcp_f32_e32 v5, v5
	s_nop 0
	v_lshlrev_b32_e32 v8, 16, v186
	v_and_b32_e32 v7, 0xffff0000, v79
	v_and_b32_e32 v9, 0xffff0000, v186
	v_pk_fma_f32 v[2:3], v[2:3], v[6:7], v[8:9]
	v_lshlrev_b32_e32 v6, 16, v78
	v_lshlrev_b32_e32 v8, 16, v187
	v_and_b32_e32 v7, 0xffff0000, v78
	v_and_b32_e32 v9, 0xffff0000, v187
	v_rcp_f32_e32 v4, v4
	s_nop 0
	v_pk_fma_f32 v[4:5], v[4:5], v[6:7], v[8:9]
	v_cvt_pk_bf16_f32 v186, v2, v3
	v_cvt_pk_bf16_f32 v187, v4, v5
	s_cbranch_scc0 .LBB0_281
	s_mov_b64 s[2:3], 0x8000
	v_ashrrev_i32_e32 v157, 31, v156
	v_lshlrev_b64 v[2:3], 11, v[156:157]
	v_ashrrev_i32_e32 v155, 31, v154
	v_lshl_add_u64 v[2:3], s[84:85], 0, v[2:3]
	v_lshl_add_u64 v[2:3], v[154:155], 1, v[2:3]
	v_lshl_add_u64 v[4:5], v[2:3], 0, s[2:3]
	s_mov_b32 s2, 0x8000
	v_add_co_u32_e32 v6, vcc, s2, v2
	s_mov_b64 s[2:3], 0x10000
	s_nop 0
	v_addc_co_u32_e32 v7, vcc, 0, v3, vcc
	global_store_dwordx2 v[2:3], v[176:177], off
	global_store_dwordx2 v[2:3], v[180:181], off offset:32
	global_store_dwordx2 v[2:3], v[184:185], off offset:64
	global_store_dwordx2 v[2:3], v[190:191], off offset:96
	global_store_dwordx2 v[6:7], v[168:169], off
	global_store_dwordx2 v[4:5], v[170:171], off offset:32
	global_store_dwordx2 v[4:5], v[172:173], off offset:64
	global_store_dwordx2 v[4:5], v[174:175], off offset:96
	v_lshl_add_u64 v[4:5], v[2:3], 0, s[2:3]
	s_mov_b32 s2, 0x10000
	v_add_co_u32_e32 v6, vcc, s2, v2
	s_mov_b64 s[2:3], 0x18000
	s_nop 0
	v_addc_co_u32_e32 v7, vcc, 0, v3, vcc
	global_store_dwordx2 v[6:7], v[158:159], off
	global_store_dwordx2 v[4:5], v[160:161], off offset:32
	global_store_dwordx2 v[4:5], v[162:163], off offset:64
	global_store_dwordx2 v[4:5], v[164:165], off offset:96
	v_lshl_add_u64 v[4:5], v[2:3], 0, s[2:3]
	s_mov_b32 s2, 0x18000
	v_add_co_u32_e32 v2, vcc, s2, v2
	s_add_i32 s58, s58, s34
	s_add_i32 s62, s62, s63
	s_add_i32 s64, s64, s65
	v_addc_co_u32_e32 v3, vcc, 0, v3, vcc
	s_cmp_ge_i32 s58, s35
	global_store_dwordx2 v[2:3], v[178:179], off
	global_store_dwordx2 v[4:5], v[182:183], off offset:32
	global_store_dwordx2 v[4:5], v[188:189], off offset:64
	global_store_dwordx2 v[4:5], v[186:187], off offset:96
	s_cbranch_scc0 .LBB0_280
